# ms_item: the four tokens' gate loads issued together under the first wait (were 4 serialized round trips); the 4 output-gate loads of the tail issued together (were 4 serialized load-wait-store); stac
# speedup vs baseline: 1.0184x; 1.0014x over previous
; #define LAS __attribute__((address_space(3)))
; __device__ __forceinline__ float bf2f(unsigned b) { return __uint_as_float(b << 16); }
; __device__ __forceinline__ float log_sigmoid(float x) { return fminf(x, 0.f) - log1pf(expf(-fabsf(x))); }
; __device__ __forceinline__ void ms_item(CArgs& A, Frame& F, int L, int item) {
;     const int b = item >> 2, h = item & 3; const int tok0 = TP + b * 4;
;     LAS float* sq = (LAS float*)(F.lds + MS_Q); LAS float* sk = (LAS float*)(F.lds + MS_K); LAS float* sv = (LAS float*)(F.lds + MS_V); LAS float* sS = (LAS float*)(F.lds + MS_S);
;     LAS float* red = (LAS float*)(F.lds + MS_RED); LAS float* lnb = (LAS float*)(F.lds + MS_LN);
;     const size_t sidx = ((size_t)L * 128 + b) * 4 + h;
;     const float* C0 = A.in[2] + sidx * 32768; const float* n0 = A.in[3] + sidx * 128; const float m0 = A.in[4][sidx];
;     const bf16* Qm = WSP(bf16, WS_QM); const bf16* Km = WSP(bf16, WS_KM); const bf16* Vm = WSP(bf16, WS_VM); const float* igfg = WSP(float, WS_IGFG);
;     { const int t = F.tid >> 7, d = F.tid & 127; sq[F.tid] = bf2f(Qm[(size_t)(tok0 + t) * 512 + h * 128 + d]); sk[F.tid] = bf2f(Km[(size_t)(tok0 + t) * 512 + h * 128 + d]); }
; #pragma unroll
;     for (int i = 0; i < 2; ++i) { const int idx = F.tid + NT * i, t = idx >> 8, vc = idx & 255; sv[idx] = bf2f(Vm[(size_t)(tok0 + t) * 1024 + h * 256 + vc]); }
;     float ig[4], bc[4], a[4], M[4], wint[4], elim[4], ksc[4];
;     { float run = 0.f, pm = -INFINITY;
; #pragma unroll
;       for (int t = 0; t < 4; ++t) { ig[t] = igfg[(size_t)(tok0 + t) * 8 + h]; run += log_sigmoid(igfg[(size_t)(tok0 + t) * 8 + 4 + h]); bc[t] = run; a[t] = ig[t] - run; pm = fmaxf(pm, a[t]);
;           M[t] = fmaxf(m0, pm); wint[t] = expf(m0 - M[t]); elim[t] = expf(-(run + M[t])); } }
.LBB0_367:
	s_and_b32 s10, s97, -4
	s_add_i32 s4, s10, 0x4000
	v_add_u32_e32 v4, s4, v172
	v_ashrrev_i32_e32 v5, 31, v4
	s_and_b32 s96, s97, 3
	v_lshlrev_b64 v[4:5], 9, v[4:5]
	v_lshl_or_b32 v1, s96, 7, v4
	v_or_b32_e32 v4, v1, v104
	v_lshlrev_b64 v[4:5], 1, v[4:5]
	v_lshl_add_u64 v[6:7], s[42:43], 0, v[4:5]
	v_lshl_add_u64 v[4:5], s[2:3], 0, v[4:5]
	global_load_ushort v1, v[6:7], off
	global_load_ushort v3, v[4:5], off
	s_ashr_i32 s6, s97, 2
	s_ashr_i32 s7, s6, 31
	s_lshl_b64 s[6:7], s[6:7], 2
	s_add_u32 s5, s6, s94
	s_addc_u32 s13, s7, s95
	s_or_b32 s12, s5, s96
	s_lshl_b64 s[28:29], s[12:13], 2
	v_readlane_b32 s6, v254, 51
	v_readlane_b32 s7, v254, 52
	s_add_u32 s6, s6, s28
	v_add_u32_e32 v6, s4, v174
	s_addc_u32 s7, s7, s29
	s_lshl_b32 s8, s96, 9
	v_ashrrev_i32_e32 v7, 31, v6
	v_lshl_add_u64 v[4:5], v[106:107], 0, s[8:9]
	v_lshlrev_b64 v[6:7], 11, v[6:7]
	v_lshl_add_u64 v[6:7], v[4:5], 0, v[6:7]
	global_load_dword v0, v2, s[6:7]
	s_lshl_b32 s5, s96, 2
	v_readlane_b32 s6, v254, 53
	s_add_u32 s8, s6, s5
	s_addc_u32 s11, s89, 0
	s_ashr_i32 s5, s4, 31
	s_lshl_b64 s[6:7], s[4:5], 5
	s_add_u32 s6, s8, s6
	s_addc_u32 s7, s11, s7
	s_mov_b32 s16, 0xbfb8aa3b
	s_mov_b32 s17, 0xb2a5705f
	s_mov_b32 s74, 0x42ce8ed0
	s_mov_b32 s75, 0xc2b17218
	s_mov_b32 s73, 0x3f2aaaab
	s_mov_b32 s76, 0x3f317218
	s_add_i32 s34, s10, 0x4001
	s_ashr_i32 s35, s34, 31
	s_mov_b32 s72, 0x7f800000
	s_mov_b32 s77, 0x33800000
	s_mov_b32 s86, 0xc2ce8ed0
	s_mov_b32 s87, 0x42b17218
	s_mov_b32 s88, 0xbfb8aa3b
	global_load_dword v214, v2, s[6:7]
	global_load_dword v215, v2, s[6:7] offset:16
	global_load_dword v216, v2, s[6:7] offset:32
	global_load_dword v217, v2, s[6:7] offset:48
	global_load_dword v218, v2, s[6:7] offset:64
	global_load_dword v219, v2, s[6:7] offset:80
	global_load_dword v220, v2, s[6:7] offset:96
	global_load_dword v221, v2, s[6:7] offset:112
	s_waitcnt vmcnt(0)
	v_lshlrev_b32_e32 v1, 16, v1
	v_lshlrev_b32_e32 v3, 16, v3
	ds_write2st64_b32 v173, v1, v3 offset1:8
	global_load_ushort v1, v[6:7], off
	v_add_u32_e32 v6, s4, v175
	v_ashrrev_i32_e32 v7, 31, v6
	v_lshlrev_b64 v[6:7], 11, v[6:7]
	v_lshl_add_u64 v[4:5], v[4:5], 0, v[6:7]
	global_load_ushort v3, v[4:5], off
	s_waitcnt vmcnt(1)
	v_lshlrev_b32_e32 v1, 16, v1
	s_waitcnt vmcnt(0)
	v_lshlrev_b32_e32 v3, 16, v3
	ds_write2st64_b32 v173, v1, v3 offset0:16 offset1:24
	v_mov_b32_e32 v1, v214
	v_mov_b32_e32 v3, v215
	s_lshl_b64 s[6:7], s[34:35], 5
	s_add_u32 s6, s8, s6
	s_addc_u32 s7, s11, s7
	s_waitcnt vmcnt(0)
	v_max_f32_e32 v4, v3, v3
	v_min_f32_e32 v6, 0, v4
	v_mul_f32_e64 v4, |v3|, s16
	v_fma_f32 v5, |v3|, s16, -v4
	v_rndne_f32_e32 v7, v4
	v_fma_f32 v5, |v3|, s17, v5
	v_sub_f32_e32 v4, v4, v7
	v_add_f32_e32 v4, v4, v5
	v_exp_f32_e32 v4, v4
	v_cvt_i32_f32_e32 v5, v7
	v_cmp_ngt_f32_e64 vcc, |v3|, s74
	v_ldexp_f32 v4, v4, v5
	s_nop 0
	v_cndmask_b32_e32 v4, 0, v4, vcc
	v_cmp_nlt_f32_e64 vcc, |v3|, s75
	s_nop 1
	v_cndmask_b32_e32 v3, v247, v4, vcc
	v_add_f32_e32 v7, 1.0, v3
	v_add_f32_e32 v4, -1.0, v7
	v_sub_f32_e32 v5, v4, v7
	v_add_f32_e32 v5, 1.0, v5
	v_sub_f32_e32 v4, v3, v4
	v_add_f32_e32 v8, v4, v5
	v_frexp_mant_f32_e32 v4, v7
	v_cmp_gt_f32_e32 vcc, s73, v4
	v_cvt_f64_f32_e32 v[4:5], v7
	v_frexp_exp_i32_f64_e32 v4, v[4:5]
	v_subbrev_co_u32_e32 v4, vcc, 0, v4, vcc
	v_sub_u32_e32 v5, 0, v4
	v_ldexp_f32 v7, v7, v5
	v_ldexp_f32 v5, v8, v5
	v_add_f32_e32 v8, -1.0, v7
	v_add_f32_e32 v9, 1.0, v8
	v_sub_f32_e32 v9, v7, v9
	v_add_f32_e32 v9, v5, v9
	v_add_f32_e32 v10, v8, v9
	v_sub_f32_e32 v8, v8, v10
	v_add_f32_e32 v8, v9, v8
	v_add_f32_e32 v9, 1.0, v7
	v_add_f32_e32 v11, -1.0, v9
	v_sub_f32_e32 v7, v7, v11
	v_add_f32_e32 v5, v5, v7
	v_add_f32_e32 v7, v9, v5
	v_sub_f32_e32 v9, v9, v7
	v_add_f32_e32 v5, v5, v9
	v_rcp_f32_e32 v9, v7
	v_cvt_f32_i32_e32 v4, v4
	v_cmp_neq_f32_e32 vcc, s72, v3
	v_mul_f32_e32 v11, v10, v9
	v_mul_f32_e32 v12, v7, v11
	v_fma_f32 v13, v11, v7, -v12
	v_fmac_f32_e32 v13, v11, v5
	v_add_f32_e32 v14, v12, v13
	v_sub_f32_e32 v15, v10, v14
	v_sub_f32_e32 v10, v10, v15
	v_sub_f32_e32 v12, v14, v12
	v_sub_f32_e32 v10, v10, v14
	v_add_f32_e32 v8, v8, v10
	v_sub_f32_e32 v10, v12, v13
	v_add_f32_e32 v8, v10, v8
	v_add_f32_e32 v10, v15, v8
	v_mul_f32_e32 v12, v9, v10
	v_mul_f32_e32 v13, v7, v12
	v_fma_f32 v7, v12, v7, -v13
	v_fmac_f32_e32 v7, v12, v5
	v_sub_f32_e32 v5, v15, v10
	v_add_f32_e32 v5, v8, v5
	v_add_f32_e32 v8, v13, v7
	v_sub_f32_e32 v14, v10, v8
	v_sub_f32_e32 v10, v10, v14
	v_sub_f32_e32 v13, v8, v13
	v_sub_f32_e32 v8, v10, v8
	v_add_f32_e32 v5, v5, v8
	v_sub_f32_e32 v7, v13, v7
	v_add_f32_e32 v5, v7, v5
	v_add_f32_e32 v7, v11, v12
	v_add_f32_e32 v5, v14, v5
	v_sub_f32_e32 v8, v7, v11
	v_mul_f32_e32 v5, v9, v5
	v_sub_f32_e32 v8, v12, v8
	v_add_f32_e32 v5, v8, v5
	v_mul_f32_e32 v11, 0x3f317218, v4
	v_add_f32_e32 v8, v7, v5
	v_fma_f32 v12, v4, s76, -v11
	v_mul_f32_e32 v9, v8, v8
	v_fmac_f32_e32 v12, 0xb102e308, v4
	v_sub_f32_e32 v4, v8, v7
	v_fmamk_f32 v10, v9, 0x3e9b6dac, v227
	v_sub_f32_e32 v4, v5, v4
	v_add_f32_e32 v5, v11, v12
	v_fmaak_f32 v10, v9, v10, 0x3f2aaada
	v_sub_f32_e32 v7, v5, v11
	v_ldexp_f32 v11, v8, 1
	v_mul_f32_e32 v8, v8, v9
	v_mul_f32_e32 v8, v8, v10
	v_add_f32_e32 v9, v11, v8
	v_sub_f32_e32 v10, v9, v11
	v_ldexp_f32 v4, v4, 1
	v_sub_f32_e32 v8, v8, v10
	v_add_f32_e32 v4, v4, v8
	v_add_f32_e32 v8, v9, v4
	v_sub_f32_e32 v9, v8, v9
	v_sub_f32_e32 v4, v4, v9
	v_add_f32_e32 v9, v5, v8
	v_sub_f32_e32 v10, v9, v5
	v_sub_f32_e32 v11, v9, v10
	v_sub_f32_e32 v7, v12, v7
	v_sub_f32_e32 v5, v5, v11
	v_sub_f32_e32 v8, v8, v10
	v_add_f32_e32 v5, v8, v5
	v_add_f32_e32 v8, v7, v4
	v_sub_f32_e32 v10, v8, v7
	v_sub_f32_e32 v11, v8, v10
	v_sub_f32_e32 v7, v7, v11
	v_sub_f32_e32 v4, v4, v10
	v_add_f32_e32 v5, v8, v5
	v_add_f32_e32 v4, v4, v7
	v_add_f32_e32 v7, v9, v5
	v_sub_f32_e32 v8, v7, v9
	v_sub_f32_e32 v5, v5, v8
	v_add_f32_e32 v4, v4, v5
	v_add_f32_e32 v4, v7, v4
	v_cndmask_b32_e32 v4, v247, v4, vcc
	v_cmp_lt_f32_e64 vcc, |v3|, s77
	v_max_f32_e32 v9, v0, v0
	s_nop 0
	v_cndmask_b32_e32 v3, v4, v3, vcc
	v_mov_b32_e32 v4, v216
	v_mov_b32_e32 v5, v217
	s_add_i32 s6, s10, 0x4002
	v_sub_f32_e32 v3, v6, v3
	s_ashr_i32 s7, s6, 31
	v_add_f32_e32 v3, 0, v3
	s_lshl_b64 s[14:15], s[6:7], 5
	v_sub_f32_e32 v181, v1, v3
	s_add_u32 s14, s8, s14
	v_max_f32_e32 v6, 0xff800000, v181
	s_addc_u32 s15, s11, s15
	v_max_f32_e32 v183, v9, v6
	s_add_i32 s36, s10, 0x4003
	s_ashr_i32 s37, s36, 31
	v_add_f32_e32 v184, v3, v183
	v_sub_f32_e32 v185, v0, v183
	v_cmp_ngt_f32_e64 s[54:55], s86, v185
	v_cmp_nlt_f32_e64 s[48:49], s87, v185
	v_cmp_nlt_f32_e64 s[52:53], s74, v184
	v_cmp_ngt_f32_e64 s[50:51], s75, v184
	s_waitcnt vmcnt(0)
; __device__ __forceinline__ float log_sigmoid(float x) { return fminf(x, 0.f) - log1pf(expf(-fabsf(x))); }
; __device__ __forceinline__ void ms_item(CArgs& A, Frame& F, int L, int item) {
;     ...
;     { float run = 0.f, pm = -INFINITY;
; #pragma unroll
;       for (int t = 0; t < 4; ++t) { ig[t] = igfg[(size_t)(tok0 + t) * 8 + h]; run += log_sigmoid(igfg[(size_t)(tok0 + t) * 8 + 4 + h]); bc[t] = run; a[t] = ig[t] - run; pm = fmaxf(pm, a[t]);
;           M[t] = fmaxf(m0, pm); wint[t] = expf(m0 - M[t]); elim[t] = expf(-(run + M[t])); } }
;     const float bend = bc[3]; float gmax = -INFINITY;
; #pragma unroll
;     for (int t = 0; t < 4; ++t) gmax = fmaxf(gmax, ig[t] + bend - bc[t]);
;     const float mnew = fmaxf(bend + m0, gmax), decay = expf(bend + m0 - mnew);
	v_mul_f32_e64 v8, |v5|, s16
	v_fma_f32 v10, |v5|, s16, -v8
	v_rndne_f32_e32 v11, v8
	v_fma_f32 v10, |v5|, s17, v10
	v_sub_f32_e32 v8, v8, v11
	v_add_f32_e32 v8, v8, v10
	v_exp_f32_e32 v8, v8
	v_cvt_i32_f32_e32 v10, v11
	v_cmp_ngt_f32_e64 vcc, |v5|, s74
	v_max_f32_e32 v7, v5, v5
	v_min_f32_e32 v7, 0, v7
	v_ldexp_f32 v8, v8, v10
	v_cndmask_b32_e32 v8, 0, v8, vcc
	v_cmp_nlt_f32_e64 vcc, |v5|, s75
	s_nop 1
	v_cndmask_b32_e32 v5, v247, v8, vcc
	v_add_f32_e32 v8, 1.0, v5
	v_add_f32_e32 v10, -1.0, v8
	v_sub_f32_e32 v11, v10, v8
	v_add_f32_e32 v11, 1.0, v11
	v_sub_f32_e32 v10, v5, v10
	v_add_f32_e32 v12, v10, v11
	v_frexp_mant_f32_e32 v10, v8
	v_cmp_gt_f32_e32 vcc, s73, v10
	v_cvt_f64_f32_e32 v[10:11], v8
	v_frexp_exp_i32_f64_e32 v10, v[10:11]
	v_subbrev_co_u32_e32 v10, vcc, 0, v10, vcc
	v_sub_u32_e32 v11, 0, v10
	v_ldexp_f32 v8, v8, v11
	v_ldexp_f32 v11, v12, v11
	v_add_f32_e32 v12, -1.0, v8
	v_add_f32_e32 v13, 1.0, v12
	v_sub_f32_e32 v13, v8, v13
	v_add_f32_e32 v13, v11, v13
	v_add_f32_e32 v14, v12, v13
	v_sub_f32_e32 v12, v12, v14
	v_add_f32_e32 v12, v13, v12
	v_add_f32_e32 v13, 1.0, v8
	v_add_f32_e32 v15, -1.0, v13
	v_sub_f32_e32 v8, v8, v15
	v_add_f32_e32 v8, v11, v8
	v_add_f32_e32 v11, v13, v8
	v_sub_f32_e32 v13, v13, v11
	v_add_f32_e32 v8, v8, v13
	v_rcp_f32_e32 v13, v11
	v_cvt_f32_i32_e32 v10, v10
	v_cmp_neq_f32_e32 vcc, s72, v5
	v_mul_f32_e32 v15, v14, v13
	v_mul_f32_e32 v16, v11, v15
	v_fma_f32 v17, v15, v11, -v16
	v_fmac_f32_e32 v17, v15, v8
	v_add_f32_e32 v18, v16, v17
	v_sub_f32_e32 v19, v14, v18
	v_sub_f32_e32 v14, v14, v19
	v_sub_f32_e32 v16, v18, v16
	v_sub_f32_e32 v14, v14, v18
	v_add_f32_e32 v12, v12, v14
	v_sub_f32_e32 v14, v16, v17
	v_add_f32_e32 v12, v14, v12
	v_add_f32_e32 v14, v19, v12
	v_mul_f32_e32 v16, v13, v14
	v_mul_f32_e32 v17, v11, v16
	v_fma_f32 v11, v16, v11, -v17
	v_fmac_f32_e32 v11, v16, v8
	v_sub_f32_e32 v8, v19, v14
	v_add_f32_e32 v8, v12, v8
	v_add_f32_e32 v12, v17, v11
	v_sub_f32_e32 v18, v14, v12
	v_sub_f32_e32 v14, v14, v18
	v_sub_f32_e32 v17, v12, v17
	v_sub_f32_e32 v12, v14, v12
	v_add_f32_e32 v8, v8, v12
	v_sub_f32_e32 v11, v17, v11
	v_add_f32_e32 v8, v11, v8
	v_add_f32_e32 v11, v15, v16
	v_add_f32_e32 v8, v18, v8
	v_sub_f32_e32 v12, v11, v15
	v_mul_f32_e32 v8, v13, v8
	v_sub_f32_e32 v12, v16, v12
	v_add_f32_e32 v8, v12, v8
	v_mul_f32_e32 v15, 0x3f317218, v10
	v_add_f32_e32 v12, v11, v8
	v_fma_f32 v16, v10, s76, -v15
	v_mul_f32_e32 v13, v12, v12
	v_fmac_f32_e32 v16, 0xb102e308, v10
	v_sub_f32_e32 v10, v12, v11
	v_fmamk_f32 v14, v13, 0x3e9b6dac, v227
	v_sub_f32_e32 v8, v8, v10
	v_add_f32_e32 v10, v15, v16
	v_fmaak_f32 v14, v13, v14, 0x3f2aaada
	v_sub_f32_e32 v11, v10, v15
	v_ldexp_f32 v15, v12, 1
	v_mul_f32_e32 v12, v12, v13
	v_mul_f32_e32 v12, v12, v14
	v_add_f32_e32 v13, v15, v12
	v_sub_f32_e32 v14, v13, v15
	v_ldexp_f32 v8, v8, 1
	v_sub_f32_e32 v12, v12, v14
	v_add_f32_e32 v8, v8, v12
	v_add_f32_e32 v12, v13, v8
	v_sub_f32_e32 v13, v12, v13
	v_sub_f32_e32 v8, v8, v13
	v_add_f32_e32 v13, v10, v12
	v_sub_f32_e32 v14, v13, v10
	v_sub_f32_e32 v15, v13, v14
	v_sub_f32_e32 v11, v16, v11
	v_sub_f32_e32 v10, v10, v15
	v_sub_f32_e32 v12, v12, v14
	v_add_f32_e32 v10, v12, v10
	v_add_f32_e32 v12, v11, v8
	v_sub_f32_e32 v14, v12, v11
	v_sub_f32_e32 v15, v12, v14
	v_sub_f32_e32 v11, v11, v15
	v_sub_f32_e32 v8, v8, v14
	v_add_f32_e32 v10, v12, v10
	v_add_f32_e32 v8, v8, v11
	v_add_f32_e32 v11, v13, v10
	v_sub_f32_e32 v12, v11, v13
	v_sub_f32_e32 v10, v10, v12
	v_add_f32_e32 v8, v8, v10
	v_add_f32_e32 v8, v11, v8
	v_cndmask_b32_e32 v8, v247, v8, vcc
	v_cmp_lt_f32_e64 vcc, |v5|, s77
	s_nop 1
	v_cndmask_b32_e32 v5, v8, v5, vcc
	v_sub_f32_e32 v5, v7, v5
	v_add_f32_e32 v5, v3, v5
	v_sub_f32_e32 v182, v4, v5
	v_max_f32_e32 v8, v6, v182
	v_mov_b32_e32 v6, v218
	v_mov_b32_e32 v7, v219
	s_lshl_b64 s[14:15], s[36:37], 5
	s_add_u32 s10, s8, s14
	v_max_f32_e32 v186, v9, v8
	s_addc_u32 s11, s11, s15
	v_add_f32_e32 v187, v5, v186
	v_sub_f32_e32 v189, v0, v186
	s_mov_b32 s8, 0x3fb8aa3b
	v_readlane_b32 s14, v254, 55
	v_readlane_b32 s15, v254, 56
	v_cmp_ngt_f32_e64 s[26:27], s86, v189
	v_cmp_nlt_f32_e64 s[56:57], s87, v189
	v_cmp_nlt_f32_e64 s[60:61], s74, v187
	v_cmp_ngt_f32_e64 s[58:59], s75, v187
	s_waitcnt vmcnt(0)
	v_max_f32_e32 v10, v7, v7
	v_min_f32_e32 v12, 0, v10
	v_mul_f32_e64 v10, |v7|, s16
	v_fma_f32 v11, |v7|, s16, -v10
	v_rndne_f32_e32 v13, v10
	v_fma_f32 v11, |v7|, s17, v11
	v_sub_f32_e32 v10, v10, v13
	v_add_f32_e32 v10, v10, v11
	v_exp_f32_e32 v10, v10
	v_cvt_i32_f32_e32 v11, v13
	v_cmp_ngt_f32_e64 vcc, |v7|, s74
	v_ldexp_f32 v10, v10, v11
	s_nop 0
	v_cndmask_b32_e32 v10, 0, v10, vcc
	v_cmp_nlt_f32_e64 vcc, |v7|, s75
	s_nop 1
	v_cndmask_b32_e32 v7, v247, v10, vcc
	v_add_f32_e32 v13, 1.0, v7
	v_add_f32_e32 v10, -1.0, v13
	v_sub_f32_e32 v11, v10, v13
	v_add_f32_e32 v11, 1.0, v11
	v_sub_f32_e32 v10, v7, v10
	v_add_f32_e32 v14, v10, v11
	v_frexp_mant_f32_e32 v10, v13
	v_cmp_gt_f32_e32 vcc, s73, v10
	v_cvt_f64_f32_e32 v[10:11], v13
	v_frexp_exp_i32_f64_e32 v10, v[10:11]
	v_subbrev_co_u32_e32 v10, vcc, 0, v10, vcc
	v_sub_u32_e32 v11, 0, v10
	v_ldexp_f32 v13, v13, v11
	v_ldexp_f32 v11, v14, v11
	v_add_f32_e32 v14, -1.0, v13
	v_add_f32_e32 v15, 1.0, v14
	v_sub_f32_e32 v15, v13, v15
	v_add_f32_e32 v15, v11, v15
	v_add_f32_e32 v16, v14, v15
	v_sub_f32_e32 v14, v14, v16
	v_add_f32_e32 v14, v15, v14
	v_add_f32_e32 v15, 1.0, v13
	v_add_f32_e32 v17, -1.0, v15
	v_sub_f32_e32 v13, v13, v17
	v_add_f32_e32 v11, v11, v13
	v_add_f32_e32 v13, v15, v11
	v_sub_f32_e32 v15, v15, v13
	v_add_f32_e32 v11, v11, v15
	v_rcp_f32_e32 v15, v13
	v_cvt_f32_i32_e32 v10, v10
	v_cmp_neq_f32_e32 vcc, s72, v7
	v_mul_f32_e32 v17, v16, v15
; __device__ __forceinline__ float log_sigmoid(float x) { return fminf(x, 0.f) - log1pf(expf(-fabsf(x))); }
; __device__ __forceinline__ void ms_item(CArgs& A, Frame& F, int L, int item) {
;     ...
;     { float run = 0.f, pm = -INFINITY;
; #pragma unroll
;       for (int t = 0; t < 4; ++t) { ig[t] = igfg[(size_t)(tok0 + t) * 8 + h]; run += log_sigmoid(igfg[(size_t)(tok0 + t) * 8 + 4 + h]); bc[t] = run; a[t] = ig[t] - run; pm = fmaxf(pm, a[t]);
;           M[t] = fmaxf(m0, pm); wint[t] = expf(m0 - M[t]); elim[t] = expf(-(run + M[t])); } }
;     const float bend = bc[3]; float gmax = -INFINITY;
; #pragma unroll
;     for (int t = 0; t < 4; ++t) gmax = fmaxf(gmax, ig[t] + bend - bc[t]);
;     const float mnew = fmaxf(bend + m0, gmax), decay = expf(bend + m0 - mnew);
; #pragma unroll
;     for (int t = 0; t < 4; ++t) ksc[t] = expf(ig[t] + bend - bc[t] - mnew);
;     __syncthreads();
	v_mul_f32_e32 v18, v13, v17
	v_fma_f32 v19, v17, v13, -v18
	v_fmac_f32_e32 v19, v17, v11
	v_add_f32_e32 v20, v18, v19
	v_sub_f32_e32 v21, v16, v20
	v_sub_f32_e32 v16, v16, v21
	v_sub_f32_e32 v18, v20, v18
	v_sub_f32_e32 v16, v16, v20
	v_add_f32_e32 v14, v14, v16
	v_sub_f32_e32 v16, v18, v19
	v_add_f32_e32 v14, v16, v14
	v_add_f32_e32 v16, v21, v14
	v_mul_f32_e32 v18, v15, v16
	v_mul_f32_e32 v19, v13, v18
	v_fma_f32 v13, v18, v13, -v19
	v_fmac_f32_e32 v13, v18, v11
	v_sub_f32_e32 v11, v21, v16
	v_add_f32_e32 v11, v14, v11
	v_add_f32_e32 v14, v19, v13
	v_sub_f32_e32 v20, v16, v14
	v_sub_f32_e32 v16, v16, v20
	v_sub_f32_e32 v19, v14, v19
	v_sub_f32_e32 v14, v16, v14
	v_add_f32_e32 v11, v11, v14
	v_sub_f32_e32 v13, v19, v13
	v_add_f32_e32 v11, v13, v11
	v_add_f32_e32 v13, v17, v18
	v_add_f32_e32 v11, v20, v11
	v_sub_f32_e32 v14, v13, v17
	v_mul_f32_e32 v11, v15, v11
	v_sub_f32_e32 v14, v18, v14
	v_add_f32_e32 v11, v14, v11
	v_mul_f32_e32 v17, 0x3f317218, v10
	v_add_f32_e32 v14, v13, v11
	v_fma_f32 v18, v10, s76, -v17
	v_mul_f32_e32 v15, v14, v14
	v_fmac_f32_e32 v18, 0xb102e308, v10
	v_sub_f32_e32 v10, v14, v13
	v_fmamk_f32 v16, v15, 0x3e9b6dac, v227
	v_sub_f32_e32 v10, v11, v10
	v_add_f32_e32 v11, v17, v18
	v_fmaak_f32 v16, v15, v16, 0x3f2aaada
	v_sub_f32_e32 v13, v11, v17
	v_ldexp_f32 v17, v14, 1
	v_mul_f32_e32 v14, v14, v15
	v_mul_f32_e32 v14, v14, v16
	v_add_f32_e32 v15, v17, v14
	v_sub_f32_e32 v16, v15, v17
	v_ldexp_f32 v10, v10, 1
	v_sub_f32_e32 v14, v14, v16
	v_add_f32_e32 v10, v10, v14
	v_add_f32_e32 v14, v15, v10
	v_sub_f32_e32 v15, v14, v15
	v_sub_f32_e32 v10, v10, v15
	v_add_f32_e32 v15, v11, v14
	v_sub_f32_e32 v16, v15, v11
	v_sub_f32_e32 v17, v15, v16
	v_sub_f32_e32 v13, v18, v13
	v_sub_f32_e32 v11, v11, v17
	v_sub_f32_e32 v14, v14, v16
	v_add_f32_e32 v11, v14, v11
	v_add_f32_e32 v14, v13, v10
	v_sub_f32_e32 v16, v14, v13
	v_sub_f32_e32 v17, v14, v16
	v_sub_f32_e32 v13, v13, v17
	v_sub_f32_e32 v10, v10, v16
	v_add_f32_e32 v11, v14, v11
	v_add_f32_e32 v10, v10, v13
	v_add_f32_e32 v13, v15, v11
	v_sub_f32_e32 v14, v13, v15
	v_sub_f32_e32 v11, v11, v14
	v_add_f32_e32 v10, v10, v11
	v_add_f32_e32 v10, v13, v10
	v_cndmask_b32_e32 v10, v247, v10, vcc
	v_cmp_lt_f32_e64 vcc, |v7|, s77
	s_nop 1
	v_cndmask_b32_e32 v7, v10, v7, vcc
	v_sub_f32_e32 v7, v12, v7
	v_add_f32_e32 v7, v5, v7
	v_sub_f32_e32 v188, v6, v7
	v_max_f32_e32 v8, v8, v188
	v_max_f32_e32 v190, v9, v8
	v_mov_b32_e32 v9, v220
	v_mov_b32_e32 v11, v221
	v_sub_f32_e32 v192, v0, v190
	v_add_f32_e32 v191, v7, v190
	s_lshl_b64 s[10:11], s[12:13], 9
	v_cmp_ngt_f32_e64 s[70:71], s86, v192
	v_cmp_nlt_f32_e64 s[64:65], s87, v192
	v_cmp_nlt_f32_e64 s[68:69], s74, v191
	v_cmp_ngt_f32_e64 s[66:67], s75, v191
	s_waitcnt lgkmcnt(0)
	s_barrier
; __device__ __forceinline__ float log_sigmoid(float x) { return fminf(x, 0.f) - log1pf(expf(-fabsf(x))); }
; __device__ __forceinline__ void ms_item(CArgs& A, Frame& F, int L, int item) {
;     ...
;     { float run = 0.f, pm = -INFINITY;
; #pragma unroll
;       for (int t = 0; t < 4; ++t) { ig[t] = igfg[(size_t)(tok0 + t) * 8 + h]; run += log_sigmoid(igfg[(size_t)(tok0 + t) * 8 + 4 + h]); bc[t] = run; a[t] = ig[t] - run; pm = fmaxf(pm, a[t]);
;           M[t] = fmaxf(m0, pm); wint[t] = expf(m0 - M[t]); elim[t] = expf(-(run + M[t])); } }
;     const float bend = bc[3]; float gmax = -INFINITY;
; #pragma unroll
;     for (int t = 0; t < 4; ++t) gmax = fmaxf(gmax, ig[t] + bend - bc[t]);
;     const float mnew = fmaxf(bend + m0, gmax), decay = expf(bend + m0 - mnew);
; #pragma unroll
;     for (int t = 0; t < 4; ++t) ksc[t] = expf(ig[t] + bend - bc[t] - mnew);
;     __syncthreads();
;     for (int p = F.wave; p < 20; p += NW) {
	s_waitcnt vmcnt(0)
	v_mul_f32_e64 v12, |v11|, s16
	v_fma_f32 v13, |v11|, s16, -v12
	v_rndne_f32_e32 v14, v12
	v_fma_f32 v13, |v11|, s17, v13
	v_sub_f32_e32 v12, v12, v14
	v_add_f32_e32 v12, v12, v13
	v_exp_f32_e32 v12, v12
	v_cvt_i32_f32_e32 v13, v14
	v_cmp_ngt_f32_e64 vcc, |v11|, s74
	v_max_f32_e32 v10, v11, v11
	v_min_f32_e32 v10, 0, v10
	v_ldexp_f32 v12, v12, v13
	v_cndmask_b32_e32 v12, 0, v12, vcc
	v_cmp_nlt_f32_e64 vcc, |v11|, s75
	v_readlane_b32 s16, v254, 57
	v_readlane_b32 s18, v254, 59
	v_cndmask_b32_e32 v11, v247, v12, vcc
	v_add_f32_e32 v14, 1.0, v11
	v_add_f32_e32 v12, -1.0, v14
	v_sub_f32_e32 v13, v12, v14
	v_add_f32_e32 v13, 1.0, v13
	v_sub_f32_e32 v12, v11, v12
	v_add_f32_e32 v15, v12, v13
	v_frexp_mant_f32_e32 v12, v14
	v_cmp_gt_f32_e32 vcc, s73, v12
	v_cvt_f64_f32_e32 v[12:13], v14
	v_frexp_exp_i32_f64_e32 v12, v[12:13]
	v_subbrev_co_u32_e32 v12, vcc, 0, v12, vcc
	v_sub_u32_e32 v13, 0, v12
	v_ldexp_f32 v14, v14, v13
	v_ldexp_f32 v13, v15, v13
	v_add_f32_e32 v15, -1.0, v14
	v_add_f32_e32 v16, 1.0, v15
	v_sub_f32_e32 v16, v14, v16
	v_add_f32_e32 v16, v13, v16
	v_add_f32_e32 v17, v15, v16
	v_sub_f32_e32 v15, v15, v17
	v_add_f32_e32 v15, v16, v15
	v_add_f32_e32 v16, 1.0, v14
	v_add_f32_e32 v18, -1.0, v16
	v_sub_f32_e32 v14, v14, v18
	v_add_f32_e32 v13, v13, v14
	v_add_f32_e32 v14, v16, v13
	v_sub_f32_e32 v16, v16, v14
	v_add_f32_e32 v13, v13, v16
	v_rcp_f32_e32 v16, v14
	v_cvt_f32_i32_e32 v12, v12
	v_cmp_neq_f32_e32 vcc, s72, v11
	v_readlane_b32 s19, v254, 60
	v_mul_f32_e32 v18, v17, v16
	v_mul_f32_e32 v19, v14, v18
	v_fma_f32 v20, v18, v14, -v19
	v_fmac_f32_e32 v20, v18, v13
	v_add_f32_e32 v21, v19, v20
	v_sub_f32_e32 v22, v17, v21
	v_sub_f32_e32 v17, v17, v22
	v_sub_f32_e32 v19, v21, v19
	v_sub_f32_e32 v17, v17, v21
	v_add_f32_e32 v15, v15, v17
	v_sub_f32_e32 v17, v19, v20
	v_add_f32_e32 v15, v17, v15
	v_add_f32_e32 v17, v22, v15
	v_mul_f32_e32 v19, v16, v17
	v_mul_f32_e32 v20, v14, v19
	v_fma_f32 v14, v19, v14, -v20
	v_fmac_f32_e32 v14, v19, v13
	v_sub_f32_e32 v13, v22, v17
	v_add_f32_e32 v13, v15, v13
	v_add_f32_e32 v15, v20, v14
	v_sub_f32_e32 v21, v17, v15
	v_sub_f32_e32 v17, v17, v21
	v_sub_f32_e32 v20, v15, v20
	v_sub_f32_e32 v15, v17, v15
	v_add_f32_e32 v13, v13, v15
	v_sub_f32_e32 v14, v20, v14
	v_add_f32_e32 v13, v14, v13
	v_add_f32_e32 v14, v18, v19
	v_add_f32_e32 v13, v21, v13
	v_sub_f32_e32 v15, v14, v18
	v_mul_f32_e32 v13, v16, v13
	v_sub_f32_e32 v15, v19, v15
	v_add_f32_e32 v13, v15, v13
	v_mul_f32_e32 v18, 0x3f317218, v12
	v_add_f32_e32 v15, v14, v13
	v_fma_f32 v19, v12, s76, -v18
	v_mul_f32_e32 v16, v15, v15
	v_fmac_f32_e32 v19, 0xb102e308, v12
	v_sub_f32_e32 v12, v15, v14
	v_fmamk_f32 v17, v16, 0x3e9b6dac, v227
	v_sub_f32_e32 v12, v13, v12
	v_add_f32_e32 v13, v18, v19
	v_fmaak_f32 v17, v16, v17, 0x3f2aaada
	v_sub_f32_e32 v14, v13, v18
	v_ldexp_f32 v18, v15, 1
	v_mul_f32_e32 v15, v15, v16
	v_mul_f32_e32 v15, v15, v17
	v_add_f32_e32 v16, v18, v15
	v_sub_f32_e32 v17, v16, v18
	v_ldexp_f32 v12, v12, 1
	v_sub_f32_e32 v15, v15, v17
	v_add_f32_e32 v12, v12, v15
	v_add_f32_e32 v15, v16, v12
	v_sub_f32_e32 v16, v15, v16
	v_sub_f32_e32 v12, v12, v16
	v_add_f32_e32 v16, v13, v15
	v_sub_f32_e32 v17, v16, v13
	v_sub_f32_e32 v18, v16, v17
	v_sub_f32_e32 v14, v19, v14
	v_sub_f32_e32 v13, v13, v18
	v_sub_f32_e32 v15, v15, v17
	v_add_f32_e32 v13, v15, v13
	v_add_f32_e32 v15, v14, v12
	v_sub_f32_e32 v17, v15, v14
	v_sub_f32_e32 v18, v15, v17
	v_sub_f32_e32 v14, v14, v18
	v_sub_f32_e32 v12, v12, v17
	v_add_f32_e32 v13, v15, v13
	v_add_f32_e32 v12, v12, v14
	v_add_f32_e32 v14, v16, v13
	v_sub_f32_e32 v15, v14, v16
	v_sub_f32_e32 v13, v13, v15
	v_add_f32_e32 v12, v12, v13
	v_add_f32_e32 v12, v14, v12
	v_cndmask_b32_e32 v12, v247, v12, vcc
	v_cmp_lt_f32_e64 vcc, |v11|, s77
	s_add_u32 s10, s18, s10
	s_addc_u32 s11, s19, s11
	v_cndmask_b32_e32 v11, v12, v11, vcc
	v_sub_f32_e32 v10, v10, v11
	v_add_f32_e32 v10, v7, v10
	v_add_f32_e32 v1, v1, v10
	v_add_f32_e32 v4, v4, v10
	v_sub_f32_e32 v193, v9, v10
	v_sub_f32_e32 v1, v1, v3
	v_sub_f32_e32 v4, v4, v5
	v_add_f32_e32 v5, v6, v10
	v_max3_f32 v194, v0, v8, v193
	v_max_f32_e32 v3, 0xff800000, v1
	v_sub_f32_e32 v5, v5, v7
	v_add_f32_e32 v6, v9, v10
	v_sub_f32_e32 v200, v0, v194
	v_max3_f32 v3, v3, v4, v5
	v_sub_f32_e32 v6, v6, v10
	v_add_f32_e32 v0, v0, v10
	v_max3_f32 v3, v0, v3, v6
	v_sub_f32_e32 v7, v0, v3
	v_sub_f32_e32 v0, v1, v3
	v_mul_f32_e32 v1, 0x3fb8aa3b, v0
	v_fma_f32 v8, v0, s8, -v1
	v_rndne_f32_e32 v9, v1
	v_fmac_f32_e32 v8, 0x32a5705f, v0
	v_sub_f32_e32 v1, v1, v9
	v_add_f32_e32 v1, v1, v8
	v_exp_f32_e32 v1, v1
	v_cvt_i32_f32_e32 v8, v9
	v_cmp_ngt_f32_e32 vcc, s86, v0
	v_add_f32_e32 v195, v10, v194
	v_cmp_ngt_f32_e64 s[78:79], s86, v200
	v_ldexp_f32 v1, v1, v8
	v_cndmask_b32_e32 v1, 0, v1, vcc
	v_cmp_nlt_f32_e32 vcc, s87, v0
	v_cmp_nlt_f32_e64 s[72:73], s87, v200
	v_cmp_nlt_f32_e64 s[76:77], s74, v195
	v_cndmask_b32_e32 v0, v247, v1, vcc
	v_sub_f32_e32 v1, v4, v3
	v_mul_f32_e32 v4, 0x3fb8aa3b, v1
	v_fma_f32 v8, v1, s8, -v4
	v_rndne_f32_e32 v9, v4
	v_fmac_f32_e32 v8, 0x32a5705f, v1
	v_sub_f32_e32 v4, v4, v9
	v_add_f32_e32 v4, v4, v8
	v_exp_f32_e32 v4, v4
	v_cvt_i32_f32_e32 v8, v9
	v_cmp_ngt_f32_e32 vcc, s86, v1
	v_cmp_ngt_f32_e64 s[74:75], s75, v195
	v_readlane_b32 s17, v254, 58
	v_ldexp_f32 v4, v4, v8
	v_cndmask_b32_e32 v4, 0, v4, vcc
	v_cmp_nlt_f32_e32 vcc, s87, v1
	s_nop 1
	v_cndmask_b32_e32 v1, v247, v4, vcc
	v_sub_f32_e32 v4, v5, v3
	v_mul_f32_e32 v5, 0x3fb8aa3b, v4
	v_fma_f32 v8, v4, s8, -v5
	v_rndne_f32_e32 v9, v5
	v_fmac_f32_e32 v8, 0x32a5705f, v4
	v_sub_f32_e32 v5, v5, v9
	v_add_f32_e32 v5, v5, v8
	v_exp_f32_e32 v5, v5
	v_cvt_i32_f32_e32 v8, v9
	v_cmp_ngt_f32_e32 vcc, s86, v4
	v_ldexp_f32 v5, v5, v8
	s_nop 0
	v_cndmask_b32_e32 v5, 0, v5, vcc
	v_cmp_nlt_f32_e32 vcc, s87, v4
	v_sub_f32_e32 v4, v6, v3
	s_nop 0
	v_cndmask_b32_e32 v146, v247, v5, vcc
	v_mul_f32_e32 v5, 0x3fb8aa3b, v4
	v_fma_f32 v6, v4, s8, -v5
	v_rndne_f32_e32 v8, v5
	v_fmac_f32_e32 v6, 0x32a5705f, v4
	v_sub_f32_e32 v5, v5, v8
	v_add_f32_e32 v5, v5, v6
	v_exp_f32_e32 v5, v5
	v_cvt_i32_f32_e32 v6, v8
	v_cmp_ngt_f32_e32 vcc, s86, v4
	v_ldexp_f32 v5, v5, v6
	s_nop 0
	v_cndmask_b32_e32 v5, 0, v5, vcc
	v_cmp_nlt_f32_e32 vcc, s87, v4
	v_mul_f32_e32 v4, 0x3fb8aa3b, v7
	v_rndne_f32_e32 v6, v4
	v_cndmask_b32_e32 v147, v247, v5, vcc
	v_fma_f32 v5, v7, s8, -v4
	v_fmac_f32_e32 v5, 0x32a5705f, v7
	v_sub_f32_e32 v4, v4, v6
	v_add_f32_e32 v4, v4, v5
	v_exp_f32_e32 v4, v4
	v_cvt_i32_f32_e32 v5, v6
	v_cmp_ngt_f32_e32 vcc, s86, v7
	v_ldexp_f32 v4, v4, v5
	s_nop 0
	v_cndmask_b32_e32 v4, 0, v4, vcc
	v_cmp_nlt_f32_e32 vcc, s87, v7
	s_nop 1
	v_cndmask_b32_e32 v148, v247, v4, vcc
	s_andn2_b64 vcc, exec, s[14:15]
	s_cbranch_vccnz .LBB0_376
	v_lshl_add_u64 v[4:5], v[102:103], 2, s[10:11]
	v_readlane_b32 s8, v255, 3
	v_readlane_b32 s16, v255, 1
	v_mov_b32_e32 v6, v180
	v_readlane_b32 s17, v254, 63
	v_readlane_b32 s86, v254, 47
	s_branch .LBB0_370

; __device__ __forceinline__ unsigned f2bf(float f) { unsigned u = __float_as_uint(f); return (u + 0x7fffu + ((u >> 16) & 1u)) >> 16; }
; __device__ __forceinline__ float bf2f(unsigned b) { return __uint_as_float(b << 16); }
; __device__ __forceinline__ void ms_item(CArgs& A, Frame& F, int L, int item) {
;     ...
;     if (F.tid < 256) { const int vc = F.tid; const float gain = A.in[11][(size_t)L * D + h * 256 + vc];
; #pragma unroll
;         for (int t = 0; t < 4; ++t) { const float var = (lnb[16 + t * 4] + lnb[16 + t * 4 + 1] + lnb[16 + t * 4 + 2] + lnb[16 + t * 4 + 3]) * (1.f / 256.f);
;             const float rstd = 1.0f / sqrtf(var + LN_EPS); const size_t o = (size_t)(tok0 + t) * D + h * 256 + vc;
;             WSP(bf16, WS_YA)[o] = (bf16)f2bf(hval[t] * rstd * gain * bf2f(WSP(bf16, WS_OG)[o])); }
;     }
.LBB0_400:
	s_or_b64 exec, exec, s[10:11]
	s_waitcnt lgkmcnt(0)
	s_barrier
	s_and_saveexec_b64 s[10:11], s[46:47]
	s_cbranch_execz .LBB0_366
	v_readlane_b32 s12, v254, 45
	v_readlane_b32 s13, v254, 46
	s_load_dwordx2 s[12:13], s[12:13], 0x58
	v_lshl_add_u64 v[0:1], s[8:9], 0, v[100:101]
	s_waitcnt lgkmcnt(0)
	s_add_u32 s12, s12, s84
	s_addc_u32 s13, s13, s85
	s_lshl_b32 s8, s8, 2
	s_add_u32 s12, s12, s8
	s_addc_u32 s13, s13, 0
	s_lshl_b64 s[4:5], s[4:5], 10
	v_lshl_add_u64 v[10:11], v[0:1], 0, s[4:5]
	v_lshl_add_u64 v[8:9], v[100:101], 2, s[12:13]
	v_lshlrev_b64 v[12:13], 1, v[10:11]
	global_load_dword v3, v[8:9], off
	v_lshl_add_u64 v[8:9], s[38:39], 0, v[12:13]
	global_load_ushort v14, v[8:9], off
	global_load_ushort v222, v[8:9], off offset:2048
	v_add_co_u32_e32 v228, vcc, 0x1000, v8
	s_nop 1
	v_addc_co_u32_e32 v229, vcc, 0, v9, vcc
	global_load_ushort v223, v[228:229], off
	global_load_ushort v224, v[228:229], off offset:2048
	ds_read_b128 v[8:11], v2 offset:41536
	s_lshl_b64 s[4:5], s[34:35], 10
	s_waitcnt lgkmcnt(0)
	v_add_f32_e32 v8, v8, v9
	v_add_f32_e32 v8, v8, v10
	v_add_f32_e32 v8, v8, v11
	v_fmamk_f32 v10, v8, 0x3b800000, v252
	v_mul_f32_e32 v11, 0x4f800000, v10
	v_cmp_gt_f32_e32 vcc, s31, v10
	v_lshl_add_u64 v[8:9], s[4:5], 0, v[0:1]
	v_lshlrev_b64 v[8:9], 1, v[8:9]
	v_cndmask_b32_e32 v15, v10, v11, vcc
	v_sqrt_f32_e32 v16, v15
	v_lshl_add_u64 v[10:11], s[0:1], 0, v[12:13]
	v_cmp_class_f32_e64 s[48:49], v15, v234
	v_add_u32_e32 v12, -1, v16
	v_add_u32_e32 v13, 1, v16
	v_fma_f32 v17, -v12, v16, v15
	v_fma_f32 v18, -v13, v16, v15
	v_cmp_ge_f32_e64 s[50:51], 0, v17
	v_cmp_lt_f32_e64 s[52:53], 0, v18
	s_waitcnt vmcnt(0)
	v_lshlrev_b32_e32 v14, 16, v14
	v_cndmask_b32_e64 v12, v16, v12, s[50:51]
	v_cndmask_b32_e64 v12, v12, v13, s[52:53]
	v_mul_f32_e32 v13, 0x37800000, v12
	v_cndmask_b32_e32 v12, v12, v13, vcc
	v_cndmask_b32_e64 v15, v12, v15, s[48:49]
	v_div_scale_f32 v16, s[4:5], v15, v15, 1.0
	v_rcp_f32_e32 v17, v16
	v_div_scale_f32 v18, vcc, 1.0, v15, 1.0
	v_lshl_add_u64 v[12:13], s[38:39], 0, v[8:9]
	v_fma_f32 v19, -v16, v17, 1.0
	v_fmac_f32_e32 v17, v19, v17
	v_mul_f32_e32 v19, v18, v17
	v_fma_f32 v20, -v16, v19, v18
	v_fmac_f32_e32 v19, v20, v17
	v_fma_f32 v16, -v16, v19, v18
	v_div_fmas_f32 v16, v16, v17, v19
	v_div_fixup_f32 v15, v16, v15, 1.0
	v_mul_f32_e32 v4, v4, v15
	v_mul_f32_e32 v4, v3, v4
	v_mul_f32_e32 v4, v4, v14
	v_bfe_u32 v14, v4, 16, 1
	v_add3_u32 v4, v4, v14, s62
	global_store_short_d16_hi v[10:11], v4, off
	v_mov_b32_e32 v4, v222
	ds_read_b128 v[10:13], v2 offset:41552
	s_lshl_b64 s[4:5], s[6:7], 10
	v_lshl_add_u64 v[8:9], s[0:1], 0, v[8:9]
	s_waitcnt lgkmcnt(0)
	v_add_f32_e32 v10, v10, v11
	v_add_f32_e32 v10, v10, v12
	v_add_f32_e32 v10, v10, v13
	v_fmamk_f32 v12, v10, 0x3b800000, v252
	v_mul_f32_e32 v13, 0x4f800000, v12
	v_cmp_gt_f32_e32 vcc, s31, v12
	v_lshl_add_u64 v[10:11], s[4:5], 0, v[0:1]
	s_nop 0
	v_lshlrev_b32_e32 v4, 16, v4
	v_cndmask_b32_e32 v14, v12, v13, vcc
	v_sqrt_f32_e32 v15, v14
	v_lshlrev_b64 v[12:13], 1, v[10:11]
	v_cmp_class_f32_e64 s[48:49], v14, v234
	v_add_u32_e32 v10, -1, v15
	v_add_u32_e32 v11, 1, v15
	v_fma_f32 v16, -v10, v15, v14
	v_fma_f32 v17, -v11, v15, v14
	v_cmp_ge_f32_e64 s[50:51], 0, v16
	v_cmp_lt_f32_e64 s[52:53], 0, v17
	s_nop 0
	v_cndmask_b32_e64 v10, v15, v10, s[50:51]
	v_cndmask_b32_e64 v10, v10, v11, s[52:53]
	v_mul_f32_e32 v11, 0x37800000, v10
	v_cndmask_b32_e32 v10, v10, v11, vcc
	v_cndmask_b32_e64 v14, v10, v14, s[48:49]
	v_div_scale_f32 v15, s[4:5], v14, v14, 1.0
	v_rcp_f32_e32 v16, v15
	v_div_scale_f32 v17, vcc, 1.0, v14, 1.0
	v_lshl_add_u64 v[10:11], s[38:39], 0, v[12:13]
	v_fma_f32 v18, -v15, v16, 1.0
	v_fmac_f32_e32 v16, v18, v16
	v_mul_f32_e32 v18, v17, v16
	v_fma_f32 v19, -v15, v18, v17
	v_fmac_f32_e32 v18, v19, v16
	v_fma_f32 v15, -v15, v18, v17
	v_div_fmas_f32 v15, v15, v16, v18
	v_div_fixup_f32 v14, v15, v14, 1.0
	v_mul_f32_e32 v5, v5, v14
	v_mul_f32_e32 v5, v3, v5
	v_mul_f32_e32 v4, v5, v4
	v_bfe_u32 v5, v4, 16, 1
	v_add3_u32 v4, v4, v5, s62
	global_store_short_d16_hi v[8:9], v4, off
	v_mov_b32_e32 v14, v223
	ds_read_b128 v[8:11], v2 offset:41568
	s_lshl_b64 s[4:5], s[36:37], 10
	v_lshl_add_u64 v[0:1], s[4:5], 0, v[0:1]
	v_lshlrev_b64 v[0:1], 1, v[0:1]
	s_waitcnt lgkmcnt(0)
	v_add_f32_e32 v4, v8, v9
	v_add_f32_e32 v4, v4, v10
	v_add_f32_e32 v4, v4, v11
	v_fmamk_f32 v4, v4, 0x3b800000, v252
	v_mul_f32_e32 v5, 0x4f800000, v4
	v_cmp_gt_f32_e32 vcc, s31, v4
	s_nop 1
	v_cndmask_b32_e32 v8, v4, v5, vcc
	v_sqrt_f32_e32 v9, v8
	v_lshl_add_u64 v[4:5], s[0:1], 0, v[12:13]
	v_cmp_class_f32_e64 s[48:49], v8, v234
	v_add_u32_e32 v10, -1, v9
	v_add_u32_e32 v11, 1, v9
	v_fma_f32 v12, -v10, v9, v8
	v_fma_f32 v13, -v11, v9, v8
	v_cmp_ge_f32_e64 s[50:51], 0, v12
	v_cmp_lt_f32_e64 s[52:53], 0, v13
	s_nop 0
	v_cndmask_b32_e64 v9, v9, v10, s[50:51]
	v_cndmask_b32_e64 v9, v9, v11, s[52:53]
	v_mul_f32_e32 v10, 0x37800000, v9
	v_cndmask_b32_e32 v9, v9, v10, vcc
	v_cndmask_b32_e64 v10, v9, v8, s[48:49]
	v_div_scale_f32 v11, s[4:5], v10, v10, 1.0
	v_rcp_f32_e32 v12, v11
	v_div_scale_f32 v13, vcc, 1.0, v10, 1.0
	v_lshl_add_u64 v[8:9], s[38:39], 0, v[0:1]
	v_fma_f32 v15, -v11, v12, 1.0
	v_fmac_f32_e32 v12, v15, v12
	v_mul_f32_e32 v15, v13, v12
	v_fma_f32 v16, -v11, v15, v13
	v_fmac_f32_e32 v15, v16, v12
	v_fma_f32 v11, -v11, v15, v13
	v_div_fmas_f32 v11, v11, v12, v15
	v_div_fixup_f32 v10, v11, v10, 1.0
	v_mul_f32_e32 v6, v6, v10
	v_mul_f32_e32 v6, v3, v6
	v_lshl_add_u64 v[0:1], s[0:1], 0, v[0:1]
	s_nop 0
	v_lshlrev_b32_e32 v10, 16, v14
	v_mul_f32_e32 v6, v6, v10
	v_bfe_u32 v10, v6, 16, 1
	v_add3_u32 v6, v6, v10, s62
	global_store_short_d16_hi v[4:5], v6, off
	v_mov_b32_e32 v4, v224
	ds_read_b128 v[8:11], v2 offset:41584
	s_waitcnt lgkmcnt(0)
	v_add_f32_e32 v5, v8, v9
	v_add_f32_e32 v5, v5, v10
	v_add_f32_e32 v5, v5, v11
	v_fmamk_f32 v5, v5, 0x3b800000, v252
	v_mul_f32_e32 v6, 0x4f800000, v5
	v_cmp_gt_f32_e32 vcc, s31, v5
	s_nop 0
	v_lshlrev_b32_e32 v4, 16, v4
	v_cndmask_b32_e32 v5, v5, v6, vcc
	v_sqrt_f32_e32 v6, v5
	v_cmp_class_f32_e64 s[48:49], v5, v234
	v_add_u32_e32 v8, -1, v6
	v_add_u32_e32 v9, 1, v6
	v_fma_f32 v10, -v8, v6, v5
	v_fma_f32 v11, -v9, v6, v5
	v_cmp_ge_f32_e64 s[50:51], 0, v10
	v_cmp_lt_f32_e64 s[52:53], 0, v11
	s_nop 0
	v_cndmask_b32_e64 v6, v6, v8, s[50:51]
	v_cndmask_b32_e64 v6, v6, v9, s[52:53]
	v_mul_f32_e32 v8, 0x37800000, v6
	v_cndmask_b32_e32 v6, v6, v8, vcc
	v_cndmask_b32_e64 v5, v6, v5, s[48:49]
	v_div_scale_f32 v6, s[4:5], v5, v5, 1.0
	v_rcp_f32_e32 v8, v6
	v_div_scale_f32 v9, vcc, 1.0, v5, 1.0
	v_fma_f32 v10, -v6, v8, 1.0
	v_fmac_f32_e32 v8, v10, v8
	v_mul_f32_e32 v10, v9, v8
	v_fma_f32 v11, -v6, v10, v9
	v_fmac_f32_e32 v10, v11, v8
	v_fma_f32 v6, -v6, v10, v9
	v_div_fmas_f32 v6, v6, v8, v10
	v_div_fixup_f32 v5, v6, v5, 1.0
	v_mul_f32_e32 v5, v7, v5
	v_mul_f32_e32 v3, v3, v5
	v_mul_f32_e32 v3, v3, v4
	v_bfe_u32 v4, v3, 16, 1
	v_add3_u32 v3, v3, v4, s62
	global_store_short_d16_hi v[0:1], v3, off
	s_branch .LBB0_366

; #define LAS __attribute__((address_space(3)))
; __device__ __forceinline__ float bf2f(unsigned b) { return __uint_as_float(b << 16); }
; __device__ __forceinline__ float log_sigmoid(float x) { return fminf(x, 0.f) - log1pf(expf(-fabsf(x))); }
; __device__ __forceinline__ void ms_item(CArgs& A, Frame& F, int L, int item) {
;     const int b = item >> 2, h = item & 3; const int tok0 = TP + b * 4;
;     LAS float* sq = (LAS float*)(F.lds + MS_Q); LAS float* sk = (LAS float*)(F.lds + MS_K); LAS float* sv = (LAS float*)(F.lds + MS_V); LAS float* sS = (LAS float*)(F.lds + MS_S);
;     LAS float* red = (LAS float*)(F.lds + MS_RED); LAS float* lnb = (LAS float*)(F.lds + MS_LN);
;     const size_t sidx = ((size_t)L * 128 + b) * 4 + h;
;     const float* C0 = A.in[2] + sidx * 32768; const float* n0 = A.in[3] + sidx * 128; const float m0 = A.in[4][sidx];
;     const bf16* Qm = WSP(bf16, WS_QM); const bf16* Km = WSP(bf16, WS_KM); const bf16* Vm = WSP(bf16, WS_VM); const float* igfg = WSP(float, WS_IGFG);
;     { const int t = F.tid >> 7, d = F.tid & 127; sq[F.tid] = bf2f(Qm[(size_t)(tok0 + t) * 512 + h * 128 + d]); sk[F.tid] = bf2f(Km[(size_t)(tok0 + t) * 512 + h * 128 + d]); }
; #pragma unroll
;     for (int i = 0; i < 2; ++i) { const int idx = F.tid + NT * i, t = idx >> 8, vc = idx & 255; sv[idx] = bf2f(Vm[(size_t)(tok0 + t) * 1024 + h * 256 + vc]); }
;     float ig[4], bc[4], a[4], M[4], wint[4], elim[4], ksc[4];
;     { float run = 0.f, pm = -INFINITY;
; #pragma unroll
;       for (int t = 0; t < 4; ++t) { ig[t] = igfg[(size_t)(tok0 + t) * 8 + h]; run += log_sigmoid(igfg[(size_t)(tok0 + t) * 8 + 4 + h]); bc[t] = run; a[t] = ig[t] - run; pm = fmaxf(pm, a[t]);
;           M[t] = fmaxf(m0, pm); wint[t] = expf(m0 - M[t]); elim[t] = expf(-(run + M[t])); } }
.LBB0_677:
	s_and_b32 s10, s97, -4
	s_add_i32 s4, s10, 0x4000
	v_add_u32_e32 v4, s4, v173
	v_ashrrev_i32_e32 v5, 31, v4
	s_and_b32 s96, s97, 3
	v_lshlrev_b64 v[4:5], 9, v[4:5]
	v_lshl_or_b32 v1, s96, 7, v4
	v_or_b32_e32 v4, v1, v104
	v_lshlrev_b64 v[4:5], 1, v[4:5]
	v_lshl_add_u64 v[6:7], s[18:19], 0, v[4:5]
	v_lshl_add_u64 v[4:5], s[2:3], 0, v[4:5]
	global_load_ushort v1, v[6:7], off
	global_load_ushort v3, v[4:5], off
	s_ashr_i32 s6, s97, 2
	s_ashr_i32 s7, s6, 31
	s_lshl_b64 s[6:7], s[6:7], 2
	s_add_u32 s5, s6, s86
	s_addc_u32 s13, s7, s87
	s_or_b32 s12, s5, s96
	s_lshl_b64 s[28:29], s[12:13], 2
	v_readlane_b32 s6, v254, 57
	v_readlane_b32 s7, v254, 58
	s_add_u32 s6, s6, s28
	v_add_u32_e32 v6, s4, v175
	s_addc_u32 s7, s7, s29
	s_lshl_b32 s8, s96, 9
	v_ashrrev_i32_e32 v7, 31, v6
	v_lshl_add_u64 v[4:5], v[106:107], 0, s[8:9]
	v_lshlrev_b64 v[6:7], 11, v[6:7]
	v_lshl_add_u64 v[6:7], v[4:5], 0, v[6:7]
	global_load_dword v0, v2, s[6:7]
	s_lshl_b32 s5, s96, 2
	v_readlane_b32 s6, v254, 51
	s_add_u32 s8, s6, s5
	s_addc_u32 s11, s89, 0
	s_ashr_i32 s5, s4, 31
	s_lshl_b64 s[6:7], s[4:5], 5
	s_add_u32 s6, s8, s6
	s_addc_u32 s7, s11, s7
	s_mov_b32 s16, 0xbfb8aa3b
	s_mov_b32 s17, 0xb2a5705f
	s_mov_b32 s72, 0x42ce8ed0
	s_mov_b32 s73, 0xc2b17218
	s_mov_b32 s71, 0x3f2aaaab
	s_mov_b32 s74, 0x3f317218
	s_add_i32 s34, s10, 0x4001
	s_ashr_i32 s35, s34, 31
	s_mov_b32 s70, 0x7f800000
	s_mov_b32 s75, 0x33800000
	s_mov_b32 s78, 0xc2ce8ed0
	s_mov_b32 s79, 0x42b17218
	s_mov_b32 s88, 0xbfb8aa3b
	global_load_dword v214, v2, s[6:7]
	global_load_dword v215, v2, s[6:7] offset:16
	global_load_dword v216, v2, s[6:7] offset:32
	global_load_dword v217, v2, s[6:7] offset:48
	global_load_dword v218, v2, s[6:7] offset:64
	global_load_dword v219, v2, s[6:7] offset:80
	global_load_dword v220, v2, s[6:7] offset:96
	global_load_dword v221, v2, s[6:7] offset:112
	s_waitcnt vmcnt(0)
	v_lshlrev_b32_e32 v1, 16, v1
	v_lshlrev_b32_e32 v3, 16, v3
	ds_write2st64_b32 v174, v1, v3 offset1:8
	global_load_ushort v1, v[6:7], off
	v_add_u32_e32 v6, s4, v176
	v_ashrrev_i32_e32 v7, 31, v6
	v_lshlrev_b64 v[6:7], 11, v[6:7]
	v_lshl_add_u64 v[4:5], v[4:5], 0, v[6:7]
	global_load_ushort v3, v[4:5], off
	s_waitcnt vmcnt(1)
	v_lshlrev_b32_e32 v1, 16, v1
	s_waitcnt vmcnt(0)
	v_lshlrev_b32_e32 v3, 16, v3
	ds_write2st64_b32 v174, v1, v3 offset0:16 offset1:24
	v_mov_b32_e32 v1, v214
	v_mov_b32_e32 v3, v215
	s_lshl_b64 s[6:7], s[34:35], 5
	s_add_u32 s6, s8, s6
	s_addc_u32 s7, s11, s7
	s_waitcnt vmcnt(0)
	v_max_f32_e32 v4, v3, v3
	v_min_f32_e32 v6, 0, v4
	v_mul_f32_e64 v4, |v3|, s16
	v_fma_f32 v5, |v3|, s16, -v4
	v_rndne_f32_e32 v7, v4
	v_fma_f32 v5, |v3|, s17, v5
	v_sub_f32_e32 v4, v4, v7
	v_add_f32_e32 v4, v4, v5
	v_exp_f32_e32 v4, v4
	v_cvt_i32_f32_e32 v5, v7
	v_cmp_ngt_f32_e64 vcc, |v3|, s72
	v_ldexp_f32 v4, v4, v5
	s_nop 0
	v_cndmask_b32_e32 v4, 0, v4, vcc
	v_cmp_nlt_f32_e64 vcc, |v3|, s73
	s_nop 1
	v_cndmask_b32_e32 v3, v247, v4, vcc
	v_add_f32_e32 v7, 1.0, v3
	v_add_f32_e32 v4, -1.0, v7
	v_sub_f32_e32 v5, v4, v7
	v_add_f32_e32 v5, 1.0, v5
	v_sub_f32_e32 v4, v3, v4
	v_add_f32_e32 v8, v4, v5
	v_frexp_mant_f32_e32 v4, v7
	v_cmp_gt_f32_e32 vcc, s71, v4
	v_cvt_f64_f32_e32 v[4:5], v7
	v_frexp_exp_i32_f64_e32 v4, v[4:5]
	v_subbrev_co_u32_e32 v4, vcc, 0, v4, vcc
	v_sub_u32_e32 v5, 0, v4
	v_ldexp_f32 v7, v7, v5
	v_ldexp_f32 v5, v8, v5
	v_add_f32_e32 v8, -1.0, v7
	v_add_f32_e32 v9, 1.0, v8
	v_sub_f32_e32 v9, v7, v9
	v_add_f32_e32 v9, v5, v9
	v_add_f32_e32 v10, v8, v9
	v_sub_f32_e32 v8, v8, v10
	v_add_f32_e32 v8, v9, v8
	v_add_f32_e32 v9, 1.0, v7
	v_add_f32_e32 v11, -1.0, v9
	v_sub_f32_e32 v7, v7, v11
	v_add_f32_e32 v5, v5, v7
	v_add_f32_e32 v7, v9, v5
	v_sub_f32_e32 v9, v9, v7
	v_add_f32_e32 v5, v5, v9
	v_rcp_f32_e32 v9, v7
	v_cvt_f32_i32_e32 v4, v4
	v_cmp_neq_f32_e32 vcc, s70, v3
	v_mul_f32_e32 v11, v10, v9
	v_mul_f32_e32 v12, v7, v11
	v_fma_f32 v13, v11, v7, -v12
	v_fmac_f32_e32 v13, v11, v5
	v_add_f32_e32 v14, v12, v13
	v_sub_f32_e32 v15, v10, v14
	v_sub_f32_e32 v10, v10, v15
	v_sub_f32_e32 v12, v14, v12
	v_sub_f32_e32 v10, v10, v14
	v_add_f32_e32 v8, v8, v10
	v_sub_f32_e32 v10, v12, v13
	v_add_f32_e32 v8, v10, v8
	v_add_f32_e32 v10, v15, v8
	v_mul_f32_e32 v12, v9, v10
	v_mul_f32_e32 v13, v7, v12
	v_fma_f32 v7, v12, v7, -v13
	v_fmac_f32_e32 v7, v12, v5
	v_sub_f32_e32 v5, v15, v10
	v_add_f32_e32 v5, v8, v5
	v_add_f32_e32 v8, v13, v7
	v_sub_f32_e32 v14, v10, v8
	v_sub_f32_e32 v10, v10, v14
	v_sub_f32_e32 v13, v8, v13
	v_sub_f32_e32 v8, v10, v8
	v_add_f32_e32 v5, v5, v8
	v_sub_f32_e32 v7, v13, v7
	v_add_f32_e32 v5, v7, v5
	v_add_f32_e32 v7, v11, v12
	v_add_f32_e32 v5, v14, v5
	v_sub_f32_e32 v8, v7, v11
	v_mul_f32_e32 v5, v9, v5
	v_sub_f32_e32 v8, v12, v8
	v_add_f32_e32 v5, v8, v5
	v_mul_f32_e32 v11, 0x3f317218, v4
	v_add_f32_e32 v8, v7, v5
	v_fma_f32 v12, v4, s74, -v11
	v_mul_f32_e32 v9, v8, v8
	v_fmac_f32_e32 v12, 0xb102e308, v4
	v_sub_f32_e32 v4, v8, v7
	v_fmamk_f32 v10, v9, 0x3e9b6dac, v227
	v_sub_f32_e32 v4, v5, v4
	v_add_f32_e32 v5, v11, v12
	v_fmaak_f32 v10, v9, v10, 0x3f2aaada
	v_sub_f32_e32 v7, v5, v11
	v_ldexp_f32 v11, v8, 1
	v_mul_f32_e32 v8, v8, v9
	v_mul_f32_e32 v8, v8, v10
	v_add_f32_e32 v9, v11, v8
	v_sub_f32_e32 v10, v9, v11
	v_ldexp_f32 v4, v4, 1
	v_sub_f32_e32 v8, v8, v10
	v_add_f32_e32 v4, v4, v8
	v_add_f32_e32 v8, v9, v4
	v_sub_f32_e32 v9, v8, v9
	v_sub_f32_e32 v4, v4, v9
	v_add_f32_e32 v9, v5, v8
	v_sub_f32_e32 v10, v9, v5
	v_sub_f32_e32 v11, v9, v10
	v_sub_f32_e32 v7, v12, v7
	v_sub_f32_e32 v5, v5, v11
	v_sub_f32_e32 v8, v8, v10
	v_add_f32_e32 v5, v8, v5
	v_add_f32_e32 v8, v7, v4
	v_sub_f32_e32 v10, v8, v7
	v_sub_f32_e32 v11, v8, v10
	v_sub_f32_e32 v7, v7, v11
	v_sub_f32_e32 v4, v4, v10
	v_add_f32_e32 v5, v8, v5
	v_add_f32_e32 v4, v4, v7
	v_add_f32_e32 v7, v9, v5
	v_sub_f32_e32 v8, v7, v9
	v_sub_f32_e32 v5, v5, v8
	v_add_f32_e32 v4, v4, v5
	v_add_f32_e32 v4, v7, v4
	v_cndmask_b32_e32 v4, v247, v4, vcc
	v_cmp_lt_f32_e64 vcc, |v3|, s75
	v_max_f32_e32 v9, v0, v0
	s_nop 0
	v_cndmask_b32_e32 v3, v4, v3, vcc
	v_mov_b32_e32 v4, v216
	v_mov_b32_e32 v5, v217
	s_add_i32 s6, s10, 0x4002
	v_sub_f32_e32 v3, v6, v3
	s_ashr_i32 s7, s6, 31
	v_add_f32_e32 v3, 0, v3
	s_lshl_b64 s[14:15], s[6:7], 5
	v_sub_f32_e32 v182, v1, v3
	s_add_u32 s14, s8, s14
	v_max_f32_e32 v6, 0xff800000, v182
	s_addc_u32 s15, s11, s15
	v_max_f32_e32 v184, v9, v6
	s_add_i32 s36, s10, 0x4003
	s_ashr_i32 s37, s36, 31
	v_add_f32_e32 v185, v3, v184
	v_sub_f32_e32 v186, v0, v184
	v_cmp_ngt_f32_e64 s[52:53], s78, v186
	v_cmp_nlt_f32_e64 s[46:47], s79, v186
	v_cmp_nlt_f32_e64 s[50:51], s72, v185
	v_cmp_ngt_f32_e64 s[48:49], s73, v185
	s_waitcnt vmcnt(0)
; __device__ __forceinline__ float log_sigmoid(float x) { return fminf(x, 0.f) - log1pf(expf(-fabsf(x))); }
; __device__ __forceinline__ void ms_item(CArgs& A, Frame& F, int L, int item) {
;     ...
;     { float run = 0.f, pm = -INFINITY;
; #pragma unroll
;       for (int t = 0; t < 4; ++t) { ig[t] = igfg[(size_t)(tok0 + t) * 8 + h]; run += log_sigmoid(igfg[(size_t)(tok0 + t) * 8 + 4 + h]); bc[t] = run; a[t] = ig[t] - run; pm = fmaxf(pm, a[t]);
;           M[t] = fmaxf(m0, pm); wint[t] = expf(m0 - M[t]); elim[t] = expf(-(run + M[t])); } }
;     const float bend = bc[3]; float gmax = -INFINITY;
; #pragma unroll
;     for (int t = 0; t < 4; ++t) gmax = fmaxf(gmax, ig[t] + bend - bc[t]);
;     const float mnew = fmaxf(bend + m0, gmax), decay = expf(bend + m0 - mnew);
	v_mul_f32_e64 v8, |v5|, s16
	v_fma_f32 v10, |v5|, s16, -v8
	v_rndne_f32_e32 v11, v8
	v_fma_f32 v10, |v5|, s17, v10
	v_sub_f32_e32 v8, v8, v11
	v_add_f32_e32 v8, v8, v10
	v_exp_f32_e32 v8, v8
	v_cvt_i32_f32_e32 v10, v11
	v_cmp_ngt_f32_e64 vcc, |v5|, s72
	v_max_f32_e32 v7, v5, v5
	v_min_f32_e32 v7, 0, v7
	v_ldexp_f32 v8, v8, v10
	v_cndmask_b32_e32 v8, 0, v8, vcc
	v_cmp_nlt_f32_e64 vcc, |v5|, s73
	s_nop 1
	v_cndmask_b32_e32 v5, v247, v8, vcc
	v_add_f32_e32 v8, 1.0, v5
	v_add_f32_e32 v10, -1.0, v8
	v_sub_f32_e32 v11, v10, v8
	v_add_f32_e32 v11, 1.0, v11
	v_sub_f32_e32 v10, v5, v10
	v_add_f32_e32 v12, v10, v11
	v_frexp_mant_f32_e32 v10, v8
	v_cmp_gt_f32_e32 vcc, s71, v10
	v_cvt_f64_f32_e32 v[10:11], v8
	v_frexp_exp_i32_f64_e32 v10, v[10:11]
	v_subbrev_co_u32_e32 v10, vcc, 0, v10, vcc
	v_sub_u32_e32 v11, 0, v10
	v_ldexp_f32 v8, v8, v11
	v_ldexp_f32 v11, v12, v11
	v_add_f32_e32 v12, -1.0, v8
	v_add_f32_e32 v13, 1.0, v12
	v_sub_f32_e32 v13, v8, v13
	v_add_f32_e32 v13, v11, v13
	v_add_f32_e32 v14, v12, v13
	v_sub_f32_e32 v12, v12, v14
	v_add_f32_e32 v12, v13, v12
	v_add_f32_e32 v13, 1.0, v8
	v_add_f32_e32 v15, -1.0, v13
	v_sub_f32_e32 v8, v8, v15
	v_add_f32_e32 v8, v11, v8
	v_add_f32_e32 v11, v13, v8
	v_sub_f32_e32 v13, v13, v11
	v_add_f32_e32 v8, v8, v13
	v_rcp_f32_e32 v13, v11
	v_cvt_f32_i32_e32 v10, v10
	v_cmp_neq_f32_e32 vcc, s70, v5
	v_mul_f32_e32 v15, v14, v13
	v_mul_f32_e32 v16, v11, v15
	v_fma_f32 v17, v15, v11, -v16
	v_fmac_f32_e32 v17, v15, v8
	v_add_f32_e32 v18, v16, v17
	v_sub_f32_e32 v19, v14, v18
	v_sub_f32_e32 v14, v14, v19
	v_sub_f32_e32 v16, v18, v16
	v_sub_f32_e32 v14, v14, v18
	v_add_f32_e32 v12, v12, v14
	v_sub_f32_e32 v14, v16, v17
	v_add_f32_e32 v12, v14, v12
	v_add_f32_e32 v14, v19, v12
	v_mul_f32_e32 v16, v13, v14
	v_mul_f32_e32 v17, v11, v16
	v_fma_f32 v11, v16, v11, -v17
	v_fmac_f32_e32 v11, v16, v8
	v_sub_f32_e32 v8, v19, v14
	v_add_f32_e32 v8, v12, v8
	v_add_f32_e32 v12, v17, v11
	v_sub_f32_e32 v18, v14, v12
	v_sub_f32_e32 v14, v14, v18
	v_sub_f32_e32 v17, v12, v17
	v_sub_f32_e32 v12, v14, v12
	v_add_f32_e32 v8, v8, v12
	v_sub_f32_e32 v11, v17, v11
	v_add_f32_e32 v8, v11, v8
	v_add_f32_e32 v11, v15, v16
	v_add_f32_e32 v8, v18, v8
	v_sub_f32_e32 v12, v11, v15
	v_mul_f32_e32 v8, v13, v8
	v_sub_f32_e32 v12, v16, v12
	v_add_f32_e32 v8, v12, v8
	v_mul_f32_e32 v15, 0x3f317218, v10
	v_add_f32_e32 v12, v11, v8
	v_fma_f32 v16, v10, s74, -v15
	v_mul_f32_e32 v13, v12, v12
	v_fmac_f32_e32 v16, 0xb102e308, v10
	v_sub_f32_e32 v10, v12, v11
	v_fmamk_f32 v14, v13, 0x3e9b6dac, v227
	v_sub_f32_e32 v8, v8, v10
	v_add_f32_e32 v10, v15, v16
	v_fmaak_f32 v14, v13, v14, 0x3f2aaada
	v_sub_f32_e32 v11, v10, v15
	v_ldexp_f32 v15, v12, 1
	v_mul_f32_e32 v12, v12, v13
	v_mul_f32_e32 v12, v12, v14
	v_add_f32_e32 v13, v15, v12
	v_sub_f32_e32 v14, v13, v15
	v_ldexp_f32 v8, v8, 1
	v_sub_f32_e32 v12, v12, v14
	v_add_f32_e32 v8, v8, v12
	v_add_f32_e32 v12, v13, v8
	v_sub_f32_e32 v13, v12, v13
	v_sub_f32_e32 v8, v8, v13
	v_add_f32_e32 v13, v10, v12
	v_sub_f32_e32 v14, v13, v10
	v_sub_f32_e32 v15, v13, v14
	v_sub_f32_e32 v11, v16, v11
	v_sub_f32_e32 v10, v10, v15
	v_sub_f32_e32 v12, v12, v14
	v_add_f32_e32 v10, v12, v10
	v_add_f32_e32 v12, v11, v8
	v_sub_f32_e32 v14, v12, v11
	v_sub_f32_e32 v15, v12, v14
	v_sub_f32_e32 v11, v11, v15
	v_sub_f32_e32 v8, v8, v14
	v_add_f32_e32 v10, v12, v10
	v_add_f32_e32 v8, v8, v11
	v_add_f32_e32 v11, v13, v10
	v_sub_f32_e32 v12, v11, v13
	v_sub_f32_e32 v10, v10, v12
	v_add_f32_e32 v8, v8, v10
	v_add_f32_e32 v8, v11, v8
	v_cndmask_b32_e32 v8, v247, v8, vcc
	v_cmp_lt_f32_e64 vcc, |v5|, s75
	s_nop 1
	v_cndmask_b32_e32 v5, v8, v5, vcc
	v_sub_f32_e32 v5, v7, v5
	v_add_f32_e32 v5, v3, v5
	v_sub_f32_e32 v183, v4, v5
	v_max_f32_e32 v8, v6, v183
	v_mov_b32_e32 v6, v218
	v_mov_b32_e32 v7, v219
	s_lshl_b64 s[14:15], s[36:37], 5
	s_add_u32 s10, s8, s14
	v_max_f32_e32 v187, v9, v8
	s_addc_u32 s11, s11, s15
	v_add_f32_e32 v188, v5, v187
	v_sub_f32_e32 v190, v0, v187
	s_mov_b32 s8, 0x3fb8aa3b
	s_mov_b64 s[14:15], s[42:43]
	v_cmp_ngt_f32_e64 s[60:61], s78, v190
	v_cmp_nlt_f32_e64 s[54:55], s79, v190
	v_cmp_nlt_f32_e64 s[58:59], s72, v188
	v_cmp_ngt_f32_e64 s[56:57], s73, v188
	s_waitcnt vmcnt(0)
	v_max_f32_e32 v10, v7, v7
	v_min_f32_e32 v12, 0, v10
	v_mul_f32_e64 v10, |v7|, s16
	v_fma_f32 v11, |v7|, s16, -v10
	v_rndne_f32_e32 v13, v10
	v_fma_f32 v11, |v7|, s17, v11
	v_sub_f32_e32 v10, v10, v13
	v_add_f32_e32 v10, v10, v11
	v_exp_f32_e32 v10, v10
	v_cvt_i32_f32_e32 v11, v13
	v_cmp_ngt_f32_e64 vcc, |v7|, s72
	v_ldexp_f32 v10, v10, v11
	s_nop 0
	v_cndmask_b32_e32 v10, 0, v10, vcc
	v_cmp_nlt_f32_e64 vcc, |v7|, s73
	s_nop 1
	v_cndmask_b32_e32 v7, v247, v10, vcc
	v_add_f32_e32 v13, 1.0, v7
	v_add_f32_e32 v10, -1.0, v13
	v_sub_f32_e32 v11, v10, v13
	v_add_f32_e32 v11, 1.0, v11
	v_sub_f32_e32 v10, v7, v10
	v_add_f32_e32 v14, v10, v11
	v_frexp_mant_f32_e32 v10, v13
	v_cmp_gt_f32_e32 vcc, s71, v10
	v_cvt_f64_f32_e32 v[10:11], v13
	v_frexp_exp_i32_f64_e32 v10, v[10:11]
	v_subbrev_co_u32_e32 v10, vcc, 0, v10, vcc
	v_sub_u32_e32 v11, 0, v10
	v_ldexp_f32 v13, v13, v11
	v_ldexp_f32 v11, v14, v11
	v_add_f32_e32 v14, -1.0, v13
	v_add_f32_e32 v15, 1.0, v14
	v_sub_f32_e32 v15, v13, v15
	v_add_f32_e32 v15, v11, v15
	v_add_f32_e32 v16, v14, v15
	v_sub_f32_e32 v14, v14, v16
	v_add_f32_e32 v14, v15, v14
	v_add_f32_e32 v15, 1.0, v13
	v_add_f32_e32 v17, -1.0, v15
	v_sub_f32_e32 v13, v13, v17
	v_add_f32_e32 v11, v11, v13
	v_add_f32_e32 v13, v15, v11
	v_sub_f32_e32 v15, v15, v13
	v_add_f32_e32 v11, v11, v15
	v_rcp_f32_e32 v15, v13
	v_cvt_f32_i32_e32 v10, v10
	v_cmp_neq_f32_e32 vcc, s70, v7
	v_mul_f32_e32 v17, v16, v15
	v_mul_f32_e32 v18, v13, v17
; __device__ __forceinline__ float log_sigmoid(float x) { return fminf(x, 0.f) - log1pf(expf(-fabsf(x))); }
; __device__ __forceinline__ void ms_item(CArgs& A, Frame& F, int L, int item) {
;     ...
;     { float run = 0.f, pm = -INFINITY;
; #pragma unroll
;       for (int t = 0; t < 4; ++t) { ig[t] = igfg[(size_t)(tok0 + t) * 8 + h]; run += log_sigmoid(igfg[(size_t)(tok0 + t) * 8 + 4 + h]); bc[t] = run; a[t] = ig[t] - run; pm = fmaxf(pm, a[t]);
;           M[t] = fmaxf(m0, pm); wint[t] = expf(m0 - M[t]); elim[t] = expf(-(run + M[t])); } }
;     const float bend = bc[3]; float gmax = -INFINITY;
; #pragma unroll
;     for (int t = 0; t < 4; ++t) gmax = fmaxf(gmax, ig[t] + bend - bc[t]);
;     const float mnew = fmaxf(bend + m0, gmax), decay = expf(bend + m0 - mnew);
; #pragma unroll
;     for (int t = 0; t < 4; ++t) ksc[t] = expf(ig[t] + bend - bc[t] - mnew);
;     __syncthreads();
	v_fma_f32 v19, v17, v13, -v18
	v_fmac_f32_e32 v19, v17, v11
	v_add_f32_e32 v20, v18, v19
	v_sub_f32_e32 v21, v16, v20
	v_sub_f32_e32 v16, v16, v21
	v_sub_f32_e32 v18, v20, v18
	v_sub_f32_e32 v16, v16, v20
	v_add_f32_e32 v14, v14, v16
	v_sub_f32_e32 v16, v18, v19
	v_add_f32_e32 v14, v16, v14
	v_add_f32_e32 v16, v21, v14
	v_mul_f32_e32 v18, v15, v16
	v_mul_f32_e32 v19, v13, v18
	v_fma_f32 v13, v18, v13, -v19
	v_fmac_f32_e32 v13, v18, v11
	v_sub_f32_e32 v11, v21, v16
	v_add_f32_e32 v11, v14, v11
	v_add_f32_e32 v14, v19, v13
	v_sub_f32_e32 v20, v16, v14
	v_sub_f32_e32 v16, v16, v20
	v_sub_f32_e32 v19, v14, v19
	v_sub_f32_e32 v14, v16, v14
	v_add_f32_e32 v11, v11, v14
	v_sub_f32_e32 v13, v19, v13
	v_add_f32_e32 v11, v13, v11
	v_add_f32_e32 v13, v17, v18
	v_add_f32_e32 v11, v20, v11
	v_sub_f32_e32 v14, v13, v17
	v_mul_f32_e32 v11, v15, v11
	v_sub_f32_e32 v14, v18, v14
	v_add_f32_e32 v11, v14, v11
	v_mul_f32_e32 v17, 0x3f317218, v10
	v_add_f32_e32 v14, v13, v11
	v_fma_f32 v18, v10, s74, -v17
	v_mul_f32_e32 v15, v14, v14
	v_fmac_f32_e32 v18, 0xb102e308, v10
	v_sub_f32_e32 v10, v14, v13
	v_fmamk_f32 v16, v15, 0x3e9b6dac, v227
	v_sub_f32_e32 v10, v11, v10
	v_add_f32_e32 v11, v17, v18
	v_fmaak_f32 v16, v15, v16, 0x3f2aaada
	v_sub_f32_e32 v13, v11, v17
	v_ldexp_f32 v17, v14, 1
	v_mul_f32_e32 v14, v14, v15
	v_mul_f32_e32 v14, v14, v16
	v_add_f32_e32 v15, v17, v14
	v_sub_f32_e32 v16, v15, v17
	v_ldexp_f32 v10, v10, 1
	v_sub_f32_e32 v14, v14, v16
	v_add_f32_e32 v10, v10, v14
	v_add_f32_e32 v14, v15, v10
	v_sub_f32_e32 v15, v14, v15
	v_sub_f32_e32 v10, v10, v15
	v_add_f32_e32 v15, v11, v14
	v_sub_f32_e32 v16, v15, v11
	v_sub_f32_e32 v17, v15, v16
	v_sub_f32_e32 v13, v18, v13
	v_sub_f32_e32 v11, v11, v17
	v_sub_f32_e32 v14, v14, v16
	v_add_f32_e32 v11, v14, v11
	v_add_f32_e32 v14, v13, v10
	v_sub_f32_e32 v16, v14, v13
	v_sub_f32_e32 v17, v14, v16
	v_sub_f32_e32 v13, v13, v17
	v_sub_f32_e32 v10, v10, v16
	v_add_f32_e32 v11, v14, v11
	v_add_f32_e32 v10, v10, v13
	v_add_f32_e32 v13, v15, v11
	v_sub_f32_e32 v14, v13, v15
	v_sub_f32_e32 v11, v11, v14
	v_add_f32_e32 v10, v10, v11
	v_add_f32_e32 v10, v13, v10
	v_cndmask_b32_e32 v10, v247, v10, vcc
	v_cmp_lt_f32_e64 vcc, |v7|, s75
	s_nop 1
	v_cndmask_b32_e32 v7, v10, v7, vcc
	v_sub_f32_e32 v7, v12, v7
	v_add_f32_e32 v7, v5, v7
	v_sub_f32_e32 v189, v6, v7
	v_max_f32_e32 v8, v8, v189
	v_max_f32_e32 v191, v9, v8
	v_mov_b32_e32 v9, v220
	v_mov_b32_e32 v11, v221
	v_sub_f32_e32 v193, v0, v191
	v_add_f32_e32 v192, v7, v191
	s_lshl_b64 s[10:11], s[12:13], 9
	s_add_u32 s10, s14, s10
	s_addc_u32 s11, s15, s11
	v_readlane_b32 s14, v254, 53
	v_readlane_b32 s15, v254, 54
	v_cmp_ngt_f32_e64 s[68:69], s78, v193
	v_cmp_nlt_f32_e64 s[26:27], s79, v193
	v_cmp_nlt_f32_e64 s[66:67], s72, v192
	v_cmp_ngt_f32_e64 s[64:65], s73, v192
	s_waitcnt lgkmcnt(0)
	s_barrier
; __device__ __forceinline__ float log_sigmoid(float x) { return fminf(x, 0.f) - log1pf(expf(-fabsf(x))); }
; __device__ __forceinline__ void ms_item(CArgs& A, Frame& F, int L, int item) {
;     ...
;     { float run = 0.f, pm = -INFINITY;
; #pragma unroll
;       for (int t = 0; t < 4; ++t) { ig[t] = igfg[(size_t)(tok0 + t) * 8 + h]; run += log_sigmoid(igfg[(size_t)(tok0 + t) * 8 + 4 + h]); bc[t] = run; a[t] = ig[t] - run; pm = fmaxf(pm, a[t]);
;           M[t] = fmaxf(m0, pm); wint[t] = expf(m0 - M[t]); elim[t] = expf(-(run + M[t])); } }
;     const float bend = bc[3]; float gmax = -INFINITY;
; #pragma unroll
;     for (int t = 0; t < 4; ++t) gmax = fmaxf(gmax, ig[t] + bend - bc[t]);
;     const float mnew = fmaxf(bend + m0, gmax), decay = expf(bend + m0 - mnew);
; #pragma unroll
;     for (int t = 0; t < 4; ++t) ksc[t] = expf(ig[t] + bend - bc[t] - mnew);
;     __syncthreads();
;     for (int p = F.wave; p < 20; p += NW) {
	s_waitcnt vmcnt(0)
	v_mul_f32_e64 v12, |v11|, s16
	v_fma_f32 v13, |v11|, s16, -v12
	v_rndne_f32_e32 v14, v12
	v_fma_f32 v13, |v11|, s17, v13
	v_sub_f32_e32 v12, v12, v14
	v_add_f32_e32 v12, v12, v13
	v_exp_f32_e32 v12, v12
	v_cvt_i32_f32_e32 v13, v14
	v_cmp_ngt_f32_e64 vcc, |v11|, s72
	v_max_f32_e32 v10, v11, v11
	v_min_f32_e32 v10, 0, v10
	v_ldexp_f32 v12, v12, v13
	v_cndmask_b32_e32 v12, 0, v12, vcc
	v_cmp_nlt_f32_e64 vcc, |v11|, s73
	s_nop 1
	v_cndmask_b32_e32 v11, v247, v12, vcc
	v_add_f32_e32 v14, 1.0, v11
	v_add_f32_e32 v12, -1.0, v14
	v_sub_f32_e32 v13, v12, v14
	v_add_f32_e32 v13, 1.0, v13
	v_sub_f32_e32 v12, v11, v12
	v_add_f32_e32 v15, v12, v13
	v_frexp_mant_f32_e32 v12, v14
	v_cmp_gt_f32_e32 vcc, s71, v12
	v_cvt_f64_f32_e32 v[12:13], v14
	v_frexp_exp_i32_f64_e32 v12, v[12:13]
	v_subbrev_co_u32_e32 v12, vcc, 0, v12, vcc
	v_sub_u32_e32 v13, 0, v12
	v_ldexp_f32 v14, v14, v13
	v_ldexp_f32 v13, v15, v13
	v_add_f32_e32 v15, -1.0, v14
	v_add_f32_e32 v16, 1.0, v15
	v_sub_f32_e32 v16, v14, v16
	v_add_f32_e32 v16, v13, v16
	v_add_f32_e32 v17, v15, v16
	v_sub_f32_e32 v15, v15, v17
	v_add_f32_e32 v15, v16, v15
	v_add_f32_e32 v16, 1.0, v14
	v_add_f32_e32 v18, -1.0, v16
	v_sub_f32_e32 v14, v14, v18
	v_add_f32_e32 v13, v13, v14
	v_add_f32_e32 v14, v16, v13
	v_sub_f32_e32 v16, v16, v14
	v_add_f32_e32 v13, v13, v16
	v_rcp_f32_e32 v16, v14
	v_cvt_f32_i32_e32 v12, v12
	v_cmp_neq_f32_e32 vcc, s70, v11
	v_mul_f32_e32 v18, v17, v16
	v_mul_f32_e32 v19, v14, v18
	v_fma_f32 v20, v18, v14, -v19
	v_fmac_f32_e32 v20, v18, v13
	v_add_f32_e32 v21, v19, v20
	v_sub_f32_e32 v22, v17, v21
	v_sub_f32_e32 v17, v17, v22
	v_sub_f32_e32 v19, v21, v19
	v_sub_f32_e32 v17, v17, v21
	v_add_f32_e32 v15, v15, v17
	v_sub_f32_e32 v17, v19, v20
	v_add_f32_e32 v15, v17, v15
	v_add_f32_e32 v17, v22, v15
	v_mul_f32_e32 v19, v16, v17
	v_mul_f32_e32 v20, v14, v19
	v_fma_f32 v14, v19, v14, -v20
	v_fmac_f32_e32 v14, v19, v13
	v_sub_f32_e32 v13, v22, v17
	v_add_f32_e32 v13, v15, v13
	v_add_f32_e32 v15, v20, v14
	v_sub_f32_e32 v21, v17, v15
	v_sub_f32_e32 v17, v17, v21
	v_sub_f32_e32 v20, v15, v20
	v_sub_f32_e32 v15, v17, v15
	v_add_f32_e32 v13, v13, v15
	v_sub_f32_e32 v14, v20, v14
	v_add_f32_e32 v13, v14, v13
	v_add_f32_e32 v14, v18, v19
	v_add_f32_e32 v13, v21, v13
	v_sub_f32_e32 v15, v14, v18
	v_mul_f32_e32 v13, v16, v13
	v_sub_f32_e32 v15, v19, v15
	v_add_f32_e32 v13, v15, v13
	v_mul_f32_e32 v18, 0x3f317218, v12
	v_add_f32_e32 v15, v14, v13
	v_fma_f32 v19, v12, s74, -v18
	v_mul_f32_e32 v16, v15, v15
	v_fmac_f32_e32 v19, 0xb102e308, v12
	v_sub_f32_e32 v12, v15, v14
	v_fmamk_f32 v17, v16, 0x3e9b6dac, v227
	v_sub_f32_e32 v12, v13, v12
	v_add_f32_e32 v13, v18, v19
	v_fmaak_f32 v17, v16, v17, 0x3f2aaada
	v_sub_f32_e32 v14, v13, v18
	v_ldexp_f32 v18, v15, 1
	v_mul_f32_e32 v15, v15, v16
	v_mul_f32_e32 v15, v15, v17
	v_add_f32_e32 v16, v18, v15
	v_sub_f32_e32 v17, v16, v18
	v_ldexp_f32 v12, v12, 1
	v_sub_f32_e32 v15, v15, v17
	v_add_f32_e32 v12, v12, v15
	v_add_f32_e32 v15, v16, v12
	v_sub_f32_e32 v16, v15, v16
	v_sub_f32_e32 v12, v12, v16
	v_add_f32_e32 v16, v13, v15
	v_sub_f32_e32 v17, v16, v13
	v_sub_f32_e32 v18, v16, v17
	v_sub_f32_e32 v14, v19, v14
	v_sub_f32_e32 v13, v13, v18
	v_sub_f32_e32 v15, v15, v17
	v_add_f32_e32 v13, v15, v13
	v_add_f32_e32 v15, v14, v12
	v_sub_f32_e32 v17, v15, v14
	v_sub_f32_e32 v18, v15, v17
	v_sub_f32_e32 v14, v14, v18
	v_sub_f32_e32 v12, v12, v17
	v_add_f32_e32 v13, v15, v13
	v_add_f32_e32 v12, v12, v14
	v_add_f32_e32 v14, v16, v13
	v_sub_f32_e32 v15, v14, v16
	v_sub_f32_e32 v13, v13, v15
	v_add_f32_e32 v12, v12, v13
	v_add_f32_e32 v12, v14, v12
	v_cndmask_b32_e32 v12, v247, v12, vcc
	v_cmp_lt_f32_e64 vcc, |v11|, s75
	s_nop 1
	v_cndmask_b32_e32 v11, v12, v11, vcc
	v_sub_f32_e32 v10, v10, v11
	v_add_f32_e32 v10, v7, v10
	v_add_f32_e32 v1, v1, v10
	v_add_f32_e32 v4, v4, v10
	v_sub_f32_e32 v194, v9, v10
	v_sub_f32_e32 v1, v1, v3
	v_sub_f32_e32 v4, v4, v5
	v_add_f32_e32 v5, v6, v10
	v_max3_f32 v195, v0, v8, v194
	v_max_f32_e32 v3, 0xff800000, v1
	v_sub_f32_e32 v5, v5, v7
	v_add_f32_e32 v6, v9, v10
	v_sub_f32_e32 v202, v0, v195
	v_max3_f32 v3, v3, v4, v5
	v_sub_f32_e32 v6, v6, v10
	v_add_f32_e32 v0, v0, v10
	v_max3_f32 v3, v0, v3, v6
	v_sub_f32_e32 v7, v0, v3
	v_sub_f32_e32 v0, v1, v3
	v_mul_f32_e32 v1, 0x3fb8aa3b, v0
	v_fma_f32 v8, v0, s8, -v1
	v_rndne_f32_e32 v9, v1
	v_fmac_f32_e32 v8, 0x32a5705f, v0
	v_sub_f32_e32 v1, v1, v9
	v_add_f32_e32 v1, v1, v8
	v_exp_f32_e32 v1, v1
	v_cvt_i32_f32_e32 v8, v9
	v_cmp_ngt_f32_e32 vcc, s78, v0
	v_add_f32_e32 v200, v10, v195
	v_cmp_ngt_f32_e64 s[76:77], s78, v202
	v_ldexp_f32 v1, v1, v8
	v_cndmask_b32_e32 v1, 0, v1, vcc
	v_cmp_nlt_f32_e32 vcc, s79, v0
	v_cmp_nlt_f32_e64 s[70:71], s79, v202
	v_cmp_nlt_f32_e64 s[74:75], s72, v200
	v_cndmask_b32_e32 v0, v247, v1, vcc
	v_sub_f32_e32 v1, v4, v3
	v_mul_f32_e32 v4, 0x3fb8aa3b, v1
	v_fma_f32 v8, v1, s8, -v4
	v_rndne_f32_e32 v9, v4
	v_fmac_f32_e32 v8, 0x32a5705f, v1
	v_sub_f32_e32 v4, v4, v9
	v_add_f32_e32 v4, v4, v8
	v_exp_f32_e32 v4, v4
	v_cvt_i32_f32_e32 v8, v9
	v_cmp_ngt_f32_e32 vcc, s78, v1
	v_cmp_ngt_f32_e64 s[72:73], s73, v200
	v_ldexp_f32 v4, v4, v8
	v_cndmask_b32_e32 v4, 0, v4, vcc
	v_cmp_nlt_f32_e32 vcc, s79, v1
	s_nop 1
	v_cndmask_b32_e32 v1, v247, v4, vcc
	v_sub_f32_e32 v4, v5, v3
	v_mul_f32_e32 v5, 0x3fb8aa3b, v4
	v_fma_f32 v8, v4, s8, -v5
	v_rndne_f32_e32 v9, v5
	v_fmac_f32_e32 v8, 0x32a5705f, v4
	v_sub_f32_e32 v5, v5, v9
	v_add_f32_e32 v5, v5, v8
	v_exp_f32_e32 v5, v5
	v_cvt_i32_f32_e32 v8, v9
	v_cmp_ngt_f32_e32 vcc, s78, v4
	v_ldexp_f32 v5, v5, v8
	s_nop 0
	v_cndmask_b32_e32 v5, 0, v5, vcc
	v_cmp_nlt_f32_e32 vcc, s79, v4
	v_sub_f32_e32 v4, v6, v3
	s_nop 0
	v_cndmask_b32_e32 v146, v247, v5, vcc
	v_mul_f32_e32 v5, 0x3fb8aa3b, v4
	v_fma_f32 v6, v4, s8, -v5
	v_rndne_f32_e32 v8, v5
	v_fmac_f32_e32 v6, 0x32a5705f, v4
	v_sub_f32_e32 v5, v5, v8
	v_add_f32_e32 v5, v5, v6
	v_exp_f32_e32 v5, v5
	v_cvt_i32_f32_e32 v6, v8
	v_cmp_ngt_f32_e32 vcc, s78, v4
	v_ldexp_f32 v5, v5, v6
	s_nop 0
	v_cndmask_b32_e32 v5, 0, v5, vcc
	v_cmp_nlt_f32_e32 vcc, s79, v4
	v_mul_f32_e32 v4, 0x3fb8aa3b, v7
	v_rndne_f32_e32 v6, v4
	v_cndmask_b32_e32 v147, v247, v5, vcc
	v_fma_f32 v5, v7, s8, -v4
	v_fmac_f32_e32 v5, 0x32a5705f, v7
	v_sub_f32_e32 v4, v4, v6
	v_add_f32_e32 v4, v4, v5
	v_exp_f32_e32 v4, v4
	v_cvt_i32_f32_e32 v5, v6
	v_cmp_ngt_f32_e32 vcc, s78, v7
	v_ldexp_f32 v4, v4, v5
	s_nop 0
	v_cndmask_b32_e32 v4, 0, v4, vcc
	v_cmp_nlt_f32_e32 vcc, s79, v7
	s_nop 1
	v_cndmask_b32_e32 v148, v247, v4, vcc
	s_andn2_b64 vcc, exec, s[14:15]
	s_cbranch_vccnz .LBB0_686
	v_lshl_add_u64 v[4:5], v[102:103], 2, s[10:11]
	v_readlane_b32 s8, v255, 1
	v_readlane_b32 s16, v254, 63
	v_mov_b32_e32 v6, v181
	v_readlane_b32 s17, v254, 61
	v_readlane_b32 s78, v254, 47
	s_branch .LBB0_680

; __device__ __forceinline__ unsigned f2bf(float f) { unsigned u = __float_as_uint(f); return (u + 0x7fffu + ((u >> 16) & 1u)) >> 16; }
; __device__ __forceinline__ float bf2f(unsigned b) { return __uint_as_float(b << 16); }
; __device__ __forceinline__ void ms_item(CArgs& A, Frame& F, int L, int item) {
;     ...
;     if (F.tid < 256) { const int vc = F.tid; const float gain = A.in[11][(size_t)L * D + h * 256 + vc];
; #pragma unroll
;         for (int t = 0; t < 4; ++t) { const float var = (lnb[16 + t * 4] + lnb[16 + t * 4 + 1] + lnb[16 + t * 4 + 2] + lnb[16 + t * 4 + 3]) * (1.f / 256.f);
;             const float rstd = 1.0f / sqrtf(var + LN_EPS); const size_t o = (size_t)(tok0 + t) * D + h * 256 + vc;
;             WSP(bf16, WS_YA)[o] = (bf16)f2bf(hval[t] * rstd * gain * bf2f(WSP(bf16, WS_OG)[o])); }
;     }
.LBB0_710:
	s_or_b64 exec, exec, s[10:11]
	s_waitcnt lgkmcnt(0)
	s_barrier
	s_and_saveexec_b64 s[10:11], s[44:45]
	s_cbranch_execz .LBB0_676
	v_readlane_b32 s12, v254, 45
	v_readlane_b32 s13, v254, 46
	s_load_dwordx2 s[12:13], s[12:13], 0x58
	v_lshl_add_u64 v[0:1], s[8:9], 0, v[100:101]
	s_waitcnt lgkmcnt(0)
	s_add_u32 s12, s12, s94
	s_addc_u32 s13, s13, s95
	s_lshl_b32 s8, s8, 2
	s_add_u32 s12, s12, s8
	s_addc_u32 s13, s13, 0
	s_lshl_b64 s[4:5], s[4:5], 10
	v_lshl_add_u64 v[10:11], v[0:1], 0, s[4:5]
	v_lshl_add_u64 v[8:9], v[100:101], 2, s[12:13]
	v_lshlrev_b64 v[12:13], 1, v[10:11]
	global_load_dword v3, v[8:9], off
	v_lshl_add_u64 v[8:9], s[84:85], 0, v[12:13]
	global_load_ushort v14, v[8:9], off
	global_load_ushort v222, v[8:9], off offset:2048
	v_add_co_u32_e32 v228, vcc, 0x1000, v8
	s_nop 1
	v_addc_co_u32_e32 v229, vcc, 0, v9, vcc
	global_load_ushort v223, v[228:229], off
	global_load_ushort v224, v[228:229], off offset:2048
	ds_read_b128 v[8:11], v2 offset:41536
	s_lshl_b64 s[4:5], s[34:35], 10
	s_waitcnt lgkmcnt(0)
	v_add_f32_e32 v8, v8, v9
	v_add_f32_e32 v8, v8, v10
	v_add_f32_e32 v8, v8, v11
	v_fmamk_f32 v10, v8, 0x3b800000, v252
	v_mul_f32_e32 v11, 0x4f800000, v10
	v_cmp_gt_f32_e32 vcc, s31, v10
	v_lshl_add_u64 v[8:9], s[4:5], 0, v[0:1]
	v_lshlrev_b64 v[8:9], 1, v[8:9]
	v_cndmask_b32_e32 v15, v10, v11, vcc
	v_sqrt_f32_e32 v16, v15
	v_lshl_add_u64 v[10:11], s[0:1], 0, v[12:13]
	v_cmp_class_f32_e64 s[46:47], v15, v234
	v_add_u32_e32 v12, -1, v16
	v_add_u32_e32 v13, 1, v16
	v_fma_f32 v17, -v12, v16, v15
	v_fma_f32 v18, -v13, v16, v15
	v_cmp_ge_f32_e64 s[48:49], 0, v17
	v_cmp_lt_f32_e64 s[50:51], 0, v18
	s_waitcnt vmcnt(0)
	v_lshlrev_b32_e32 v14, 16, v14
	v_cndmask_b32_e64 v12, v16, v12, s[48:49]
	v_cndmask_b32_e64 v12, v12, v13, s[50:51]
	v_mul_f32_e32 v13, 0x37800000, v12
	v_cndmask_b32_e32 v12, v12, v13, vcc
	v_cndmask_b32_e64 v15, v12, v15, s[46:47]
	v_div_scale_f32 v16, s[4:5], v15, v15, 1.0
	v_rcp_f32_e32 v17, v16
	v_div_scale_f32 v18, vcc, 1.0, v15, 1.0
	v_lshl_add_u64 v[12:13], s[84:85], 0, v[8:9]
	v_fma_f32 v19, -v16, v17, 1.0
	v_fmac_f32_e32 v17, v19, v17
	v_mul_f32_e32 v19, v18, v17
	v_fma_f32 v20, -v16, v19, v18
	v_fmac_f32_e32 v19, v20, v17
	v_fma_f32 v16, -v16, v19, v18
	v_div_fmas_f32 v16, v16, v17, v19
	v_div_fixup_f32 v15, v16, v15, 1.0
	v_mul_f32_e32 v4, v4, v15
	v_mul_f32_e32 v4, v3, v4
	v_mul_f32_e32 v4, v4, v14
	v_bfe_u32 v14, v4, 16, 1
	v_add3_u32 v4, v4, v14, s62
	global_store_short_d16_hi v[10:11], v4, off
	v_mov_b32_e32 v4, v222
	ds_read_b128 v[10:13], v2 offset:41552
	s_lshl_b64 s[4:5], s[6:7], 10
	v_lshl_add_u64 v[8:9], s[0:1], 0, v[8:9]
	s_waitcnt lgkmcnt(0)
	v_add_f32_e32 v10, v10, v11
	v_add_f32_e32 v10, v10, v12
	v_add_f32_e32 v10, v10, v13
	v_fmamk_f32 v12, v10, 0x3b800000, v252
	v_mul_f32_e32 v13, 0x4f800000, v12
	v_cmp_gt_f32_e32 vcc, s31, v12
	v_lshl_add_u64 v[10:11], s[4:5], 0, v[0:1]
	s_nop 0
	v_lshlrev_b32_e32 v4, 16, v4
	v_cndmask_b32_e32 v14, v12, v13, vcc
	v_sqrt_f32_e32 v15, v14
	v_lshlrev_b64 v[12:13], 1, v[10:11]
	v_cmp_class_f32_e64 s[46:47], v14, v234
	v_add_u32_e32 v10, -1, v15
	v_add_u32_e32 v11, 1, v15
	v_fma_f32 v16, -v10, v15, v14
	v_fma_f32 v17, -v11, v15, v14
	v_cmp_ge_f32_e64 s[48:49], 0, v16
	v_cmp_lt_f32_e64 s[50:51], 0, v17
	s_nop 0
	v_cndmask_b32_e64 v10, v15, v10, s[48:49]
	v_cndmask_b32_e64 v10, v10, v11, s[50:51]
	v_mul_f32_e32 v11, 0x37800000, v10
	v_cndmask_b32_e32 v10, v10, v11, vcc
	v_cndmask_b32_e64 v14, v10, v14, s[46:47]
	v_div_scale_f32 v15, s[4:5], v14, v14, 1.0
	v_rcp_f32_e32 v16, v15
	v_div_scale_f32 v17, vcc, 1.0, v14, 1.0
	v_lshl_add_u64 v[10:11], s[84:85], 0, v[12:13]
	v_fma_f32 v18, -v15, v16, 1.0
	v_fmac_f32_e32 v16, v18, v16
	v_mul_f32_e32 v18, v17, v16
	v_fma_f32 v19, -v15, v18, v17
	v_fmac_f32_e32 v18, v19, v16
	v_fma_f32 v15, -v15, v18, v17
	v_div_fmas_f32 v15, v15, v16, v18
	v_div_fixup_f32 v14, v15, v14, 1.0
	v_mul_f32_e32 v5, v5, v14
	v_mul_f32_e32 v5, v3, v5
	v_mul_f32_e32 v4, v5, v4
	v_bfe_u32 v5, v4, 16, 1
	v_add3_u32 v4, v4, v5, s62
	global_store_short_d16_hi v[8:9], v4, off
	v_mov_b32_e32 v14, v223
	ds_read_b128 v[8:11], v2 offset:41568
	s_lshl_b64 s[4:5], s[36:37], 10
	v_lshl_add_u64 v[0:1], s[4:5], 0, v[0:1]
	v_lshlrev_b64 v[0:1], 1, v[0:1]
	s_waitcnt lgkmcnt(0)
	v_add_f32_e32 v4, v8, v9
	v_add_f32_e32 v4, v4, v10
	v_add_f32_e32 v4, v4, v11
	v_fmamk_f32 v4, v4, 0x3b800000, v252
	v_mul_f32_e32 v5, 0x4f800000, v4
	v_cmp_gt_f32_e32 vcc, s31, v4
	s_nop 1
	v_cndmask_b32_e32 v8, v4, v5, vcc
	v_sqrt_f32_e32 v9, v8
	v_lshl_add_u64 v[4:5], s[0:1], 0, v[12:13]
	v_cmp_class_f32_e64 s[46:47], v8, v234
	v_add_u32_e32 v10, -1, v9
	v_add_u32_e32 v11, 1, v9
	v_fma_f32 v12, -v10, v9, v8
	v_fma_f32 v13, -v11, v9, v8
	v_cmp_ge_f32_e64 s[48:49], 0, v12
	v_cmp_lt_f32_e64 s[50:51], 0, v13
	s_nop 0
	v_cndmask_b32_e64 v9, v9, v10, s[48:49]
	v_cndmask_b32_e64 v9, v9, v11, s[50:51]
	v_mul_f32_e32 v10, 0x37800000, v9
	v_cndmask_b32_e32 v9, v9, v10, vcc
	v_cndmask_b32_e64 v10, v9, v8, s[46:47]
	v_div_scale_f32 v11, s[4:5], v10, v10, 1.0
	v_rcp_f32_e32 v12, v11
	v_div_scale_f32 v13, vcc, 1.0, v10, 1.0
	v_lshl_add_u64 v[8:9], s[84:85], 0, v[0:1]
	v_fma_f32 v15, -v11, v12, 1.0
	v_fmac_f32_e32 v12, v15, v12
	v_mul_f32_e32 v15, v13, v12
	v_fma_f32 v16, -v11, v15, v13
	v_fmac_f32_e32 v15, v16, v12
	v_fma_f32 v11, -v11, v15, v13
	v_div_fmas_f32 v11, v11, v12, v15
	v_div_fixup_f32 v10, v11, v10, 1.0
	v_mul_f32_e32 v6, v6, v10
	v_mul_f32_e32 v6, v3, v6
	v_lshl_add_u64 v[0:1], s[0:1], 0, v[0:1]
	s_nop 0
	v_lshlrev_b32_e32 v10, 16, v14
	v_mul_f32_e32 v6, v6, v10
	v_bfe_u32 v10, v6, 16, 1
	v_add3_u32 v6, v6, v10, s62
	global_store_short_d16_hi v[4:5], v6, off
	v_mov_b32_e32 v4, v224
	ds_read_b128 v[8:11], v2 offset:41584
	s_waitcnt lgkmcnt(0)
	v_add_f32_e32 v5, v8, v9
	v_add_f32_e32 v5, v5, v10
	v_add_f32_e32 v5, v5, v11
	v_fmamk_f32 v5, v5, 0x3b800000, v252
	v_mul_f32_e32 v6, 0x4f800000, v5
	v_cmp_gt_f32_e32 vcc, s31, v5
	s_nop 0
	v_lshlrev_b32_e32 v4, 16, v4
	v_cndmask_b32_e32 v5, v5, v6, vcc
	v_sqrt_f32_e32 v6, v5
	v_cmp_class_f32_e64 s[46:47], v5, v234
	v_add_u32_e32 v8, -1, v6
	v_add_u32_e32 v9, 1, v6
	v_fma_f32 v10, -v8, v6, v5
	v_fma_f32 v11, -v9, v6, v5
	v_cmp_ge_f32_e64 s[48:49], 0, v10
	v_cmp_lt_f32_e64 s[50:51], 0, v11
	s_nop 0
	v_cndmask_b32_e64 v6, v6, v8, s[48:49]
	v_cndmask_b32_e64 v6, v6, v9, s[50:51]
	v_mul_f32_e32 v8, 0x37800000, v6
	v_cndmask_b32_e32 v6, v6, v8, vcc
	v_cndmask_b32_e64 v5, v6, v5, s[46:47]
	v_div_scale_f32 v6, s[4:5], v5, v5, 1.0
	v_rcp_f32_e32 v8, v6
	v_div_scale_f32 v9, vcc, 1.0, v5, 1.0
	v_fma_f32 v10, -v6, v8, 1.0
	v_fmac_f32_e32 v8, v10, v8
	v_mul_f32_e32 v10, v9, v8
	v_fma_f32 v11, -v6, v10, v9
	v_fmac_f32_e32 v10, v11, v8
	v_fma_f32 v6, -v6, v10, v9
	v_div_fmas_f32 v6, v6, v8, v10
	v_div_fixup_f32 v5, v6, v5, 1.0
	v_mul_f32_e32 v5, v7, v5
	v_mul_f32_e32 v3, v3, v5
	v_mul_f32_e32 v3, v3, v4
	v_bfe_u32 v4, v3, 16, 1
	v_add3_u32 v3, v3, v4, s62
	global_store_short_d16_hi v[0:1], v3, off
	s_branch .LBB0_676
